# PH4 fused pool-weight reduction rewritten: scalar-loaded wave-uniform operands, w_out rows prefetched 6 groups ahead, fully unrolled
# speedup vs baseline: 1.1100x; 1.0181x over previous
; __device__ __forceinline__ KArgs kargs() { KArgs p = (KArgs)__builtin_amdgcn_kernarg_segment_ptr(); asm volatile("" : "+s"(p)); return p; }
; __global__ void __launch_bounds__(512, 2) fwd_kernel(Args a) {
;     ...
;     } else if (bx >= 130) {
;         KArgs k = kargs();
;         const float* pool_w = KIN(17); const float* pool_scale = KIN(18); const float* w_out = KIN(19); bf16* WMIX = WSP(bf16, WS_WMIX);
;         const size_t vt = (size_t)(bx - 130) * 512 + tid, VNT = (size_t)64 * 512;
;         for (size_t i = vt; i < (size_t)128 * 256; i += VNT) {
;             const int n4 = (int)(i & 255) * 4, gc0 = (int)(i >> 8) * 4, g = gc0 >> 7;
;             const float* pw = pool_w + (size_t)gc0 * 128; const float* sc = pool_scale + g * 128; const float* wo = w_out + (size_t)(512 + g * 128) * D + n4;
;             f32x4 s0 = (f32x4){0.f, 0.f, 0.f, 0.f}, s1 = s0, s2 = s0, s3 = s0;
; #pragma unroll 16
;             for (int d = 0; d < 128; ++d) {
;                 const f32x4 wv = *(const f32x4*)(wo + (size_t)d * D) * sc[d];
;                 s0 += wv * pw[d]; s1 += wv * pw[128 + d]; s2 += wv * pw[256 + d]; s3 += wv * pw[384 + d];
;             }
.LBB0_416:
	s_cmpk_lt_i32 s2, 0x82
	s_cbranch_scc1 .LBB0_422
	s_add_i32 s0, s2, 0xffffff7e
	s_mov_b32 s1, 0
	s_lshl_b64 s[0:1], s[0:1], 9
	v_lshl_add_u64 v[0:1], s[0:1], 0, v[152:153]
	s_mov_b64 s[0:1], 0x8000
	s_mov_b64 s[12:13], s[76:77]
	v_cmp_gt_u64_e32 vcc, s[0:1], v[0:1]
	s_and_saveexec_b64 s[8:9], vcc
	s_cbranch_execz .LBB0_421
	s_load_dwordx2 s[10:11], s[76:77], 0xd8
	s_load_dwordx4 s[4:7], s[76:77], 0x88
	s_load_dwordx2 s[0:1], s[76:77], 0x98
	v_lshrrev_b32_e32 v1, 6, v0
	v_and_b32_e32 v2, 0x1fc, v1
	v_and_b32_e32 v1, 0xff, v152
	v_lshlrev_b32_e32 v1, 4, v1
	v_readfirstlane_b32 s29, v0
	v_mov_b32_e32 v10, 0
	v_mov_b32_e32 v11, 0
	v_mov_b32_e32 v12, 0
	v_mov_b32_e32 v13, 0
	v_mov_b32_e32 v20, 0
	v_mov_b32_e32 v21, 0
	v_mov_b32_e32 v14, 0
	v_mov_b32_e32 v15, 0
	v_mov_b32_e32 v22, 0
	v_mov_b32_e32 v23, 0
	v_mov_b32_e32 v16, 0
	v_mov_b32_e32 v17, 0
	v_mov_b32_e32 v24, 0
	v_mov_b32_e32 v25, 0
	v_mov_b32_e32 v18, 0
	v_mov_b32_e32 v19, 0
	s_lshr_b32 s31, s29, 8
	s_lshr_b32 s89, s31, 5
	s_lshl_b32 s29, s31, 11
	s_lshl_b32 s31, s89, 9
	s_lshl_b32 s89, s89, 19
	s_waitcnt lgkmcnt(0)
	s_add_u32 s50, s0, s89
	s_addc_u32 s51, s1, 0
	s_add_u32 s50, s50, 0x201000
	s_addc_u32 s51, s51, 0
	s_add_u32 s0, s4, s29
	s_addc_u32 s1, s5, 0
	s_add_u32 s32, s6, s31
	s_addc_u32 s33, s7, 0
	s_load_dwordx4 s[4:7], s[32:33], 0x0
	s_load_dwordx4 s[12:15], s[0:1], 0x0
	s_load_dwordx4 s[16:19], s[0:1], 0x200
	s_load_dwordx4 s[36:39], s[0:1], 0x400
	s_load_dwordx4 s[64:67], s[0:1], 0x600
	global_load_dwordx4 v[32:35], v1, s[50:51] offset:-4096
	global_load_dwordx4 v[36:39], v1, s[50:51]
	s_add_u32 s50, s50, 0x2000
	s_addc_u32 s51, s51, 0
	global_load_dwordx4 v[40:43], v1, s[50:51] offset:-4096
	global_load_dwordx4 v[44:47], v1, s[50:51]
	s_add_u32 s50, s50, 0x2000
	s_addc_u32 s51, s51, 0
	global_load_dwordx4 v[48:51], v1, s[50:51] offset:-4096
	global_load_dwordx4 v[52:55], v1, s[50:51]
	s_add_u32 s50, s50, 0x2000
	s_addc_u32 s51, s51, 0
	global_load_dwordx4 v[56:59], v1, s[50:51] offset:-4096
	global_load_dwordx4 v[60:63], v1, s[50:51]
	s_add_u32 s50, s50, 0x2000
	s_addc_u32 s51, s51, 0
	global_load_dwordx4 v[64:67], v1, s[50:51] offset:-4096
	global_load_dwordx4 v[68:71], v1, s[50:51]
	s_add_u32 s50, s50, 0x2000
	s_addc_u32 s51, s51, 0
	global_load_dwordx4 v[72:75], v1, s[50:51] offset:-4096
	global_load_dwordx4 v[76:79], v1, s[50:51]
	s_add_u32 s50, s50, 0x2000
	s_addc_u32 s51, s51, 0
	global_load_dwordx4 v[80:83], v1, s[50:51] offset:-4096
	global_load_dwordx4 v[84:87], v1, s[50:51]
	s_add_u32 s50, s50, 0x2000
	s_addc_u32 s51, s51, 0
	global_load_dwordx4 v[88:91], v1, s[50:51] offset:-4096
	global_load_dwordx4 v[92:95], v1, s[50:51]
	s_add_u32 s50, s50, 0x2000
	s_addc_u32 s51, s51, 0
	global_load_dwordx4 v[96:99], v1, s[50:51] offset:-4096
	global_load_dwordx4 v[100:103], v1, s[50:51]
	s_add_u32 s50, s50, 0x2000
	s_addc_u32 s51, s51, 0
	global_load_dwordx4 v[104:107], v1, s[50:51] offset:-4096
	global_load_dwordx4 v[108:111], v1, s[50:51]
	s_add_u32 s50, s50, 0x2000
	s_addc_u32 s51, s51, 0
	global_load_dwordx4 v[112:115], v1, s[50:51] offset:-4096
	global_load_dwordx4 v[116:119], v1, s[50:51]
	s_add_u32 s50, s50, 0x2000
	s_addc_u32 s51, s51, 0
	global_load_dwordx4 v[120:123], v1, s[50:51] offset:-4096
	global_load_dwordx4 v[124:127], v1, s[50:51]
	s_add_u32 s50, s50, 0x2000
	s_addc_u32 s51, s51, 0
	s_waitcnt lgkmcnt(0)
	s_load_dwordx4 s[40:43], s[32:33], 0x10
	s_load_dwordx4 s[56:59], s[0:1], 0x10
	s_load_dwordx4 s[60:63], s[0:1], 0x210
	s_load_dwordx4 s[92:95], s[0:1], 0x410
	s_load_dwordx4 s[96:99], s[0:1], 0x610
	global_load_dwordx4 v[128:131], v1, s[50:51] offset:-4096
	global_load_dwordx4 v[132:135], v1, s[50:51]
	s_add_u32 s50, s50, 0x2000
	s_addc_u32 s51, s51, 0
	global_load_dwordx4 v[136:139], v1, s[50:51] offset:-4096
	global_load_dwordx4 v[140:143], v1, s[50:51]
	s_add_u32 s50, s50, 0x2000
	s_addc_u32 s51, s51, 0
	s_waitcnt vmcnt(24)
	v_mul_f32_e32 v32, s4, v32
	v_mul_f32_e32 v33, s4, v33
	v_mul_f32_e32 v34, s4, v34
	v_mul_f32_e32 v35, s4, v35
	v_fmac_f32_e32 v10, s12, v32
	v_fmac_f32_e32 v11, s12, v33
	v_fmac_f32_e32 v12, s12, v34
	v_fmac_f32_e32 v13, s12, v35
	v_fmac_f32_e32 v20, s16, v32
	v_fmac_f32_e32 v21, s16, v33
	v_fmac_f32_e32 v14, s16, v34
	v_fmac_f32_e32 v15, s16, v35
	v_fmac_f32_e32 v22, s36, v32
	v_fmac_f32_e32 v23, s36, v33
	v_fmac_f32_e32 v16, s36, v34
	v_fmac_f32_e32 v17, s36, v35
	v_fmac_f32_e32 v24, s64, v32
	v_fmac_f32_e32 v25, s64, v33
	v_fmac_f32_e32 v18, s64, v34
	v_fmac_f32_e32 v19, s64, v35
	v_mul_f32_e32 v36, s5, v36
	v_mul_f32_e32 v37, s5, v37
	v_mul_f32_e32 v38, s5, v38
	v_mul_f32_e32 v39, s5, v39
	v_fmac_f32_e32 v10, s13, v36
	v_fmac_f32_e32 v11, s13, v37
	v_fmac_f32_e32 v12, s13, v38
	v_fmac_f32_e32 v13, s13, v39
	v_fmac_f32_e32 v20, s17, v36
	v_fmac_f32_e32 v21, s17, v37
	v_fmac_f32_e32 v14, s17, v38
	v_fmac_f32_e32 v15, s17, v39
	v_fmac_f32_e32 v22, s37, v36
	v_fmac_f32_e32 v23, s37, v37
	v_fmac_f32_e32 v16, s37, v38
	v_fmac_f32_e32 v17, s37, v39
	v_fmac_f32_e32 v24, s65, v36
	v_fmac_f32_e32 v25, s65, v37
	v_fmac_f32_e32 v18, s65, v38
	v_fmac_f32_e32 v19, s65, v39
	v_mul_f32_e32 v40, s6, v40
	v_mul_f32_e32 v41, s6, v41
	v_mul_f32_e32 v42, s6, v42
	v_mul_f32_e32 v43, s6, v43
	v_fmac_f32_e32 v10, s14, v40
	v_fmac_f32_e32 v11, s14, v41
	v_fmac_f32_e32 v12, s14, v42
	v_fmac_f32_e32 v13, s14, v43
	v_fmac_f32_e32 v20, s18, v40
	v_fmac_f32_e32 v21, s18, v41
	v_fmac_f32_e32 v14, s18, v42
	v_fmac_f32_e32 v15, s18, v43
	v_fmac_f32_e32 v22, s38, v40
	v_fmac_f32_e32 v23, s38, v41
	v_fmac_f32_e32 v16, s38, v42
	v_fmac_f32_e32 v17, s38, v43
	v_fmac_f32_e32 v24, s66, v40
	v_fmac_f32_e32 v25, s66, v41
	v_fmac_f32_e32 v18, s66, v42
	v_fmac_f32_e32 v19, s66, v43
	v_mul_f32_e32 v44, s7, v44
	v_mul_f32_e32 v45, s7, v45
	v_mul_f32_e32 v46, s7, v46
	v_mul_f32_e32 v47, s7, v47
	v_fmac_f32_e32 v10, s15, v44
	v_fmac_f32_e32 v11, s15, v45
	v_fmac_f32_e32 v12, s15, v46
	v_fmac_f32_e32 v13, s15, v47
	v_fmac_f32_e32 v20, s19, v44
	v_fmac_f32_e32 v21, s19, v45
	v_fmac_f32_e32 v14, s19, v46
	v_fmac_f32_e32 v15, s19, v47
	v_fmac_f32_e32 v22, s39, v44
	v_fmac_f32_e32 v23, s39, v45
	v_fmac_f32_e32 v16, s39, v46
	v_fmac_f32_e32 v17, s39, v47
	v_fmac_f32_e32 v24, s67, v44
	v_fmac_f32_e32 v25, s67, v45
	v_fmac_f32_e32 v18, s67, v46
	v_fmac_f32_e32 v19, s67, v47
	s_waitcnt lgkmcnt(0)
; __global__ void __launch_bounds__(512, 2) fwd_kernel(Args a) {
;     ...
;             for (int d = 0; d < 128; ++d) {
;                 const f32x4 wv = *(const f32x4*)(wo + (size_t)d * D) * sc[d];
;                 s0 += wv * pw[d]; s1 += wv * pw[128 + d]; s2 += wv * pw[256 + d]; s3 += wv * pw[384 + d];
;             }
	s_load_dwordx4 s[4:7], s[32:33], 0x20
	s_load_dwordx4 s[12:15], s[0:1], 0x20
	s_load_dwordx4 s[16:19], s[0:1], 0x220
	s_load_dwordx4 s[36:39], s[0:1], 0x420
	s_load_dwordx4 s[64:67], s[0:1], 0x620
	global_load_dwordx4 v[32:35], v1, s[50:51] offset:-4096
	global_load_dwordx4 v[36:39], v1, s[50:51]
	s_add_u32 s50, s50, 0x2000
	s_addc_u32 s51, s51, 0
	global_load_dwordx4 v[40:43], v1, s[50:51] offset:-4096
	global_load_dwordx4 v[44:47], v1, s[50:51]
	s_add_u32 s50, s50, 0x2000
	s_addc_u32 s51, s51, 0
	s_waitcnt vmcnt(24)
	v_mul_f32_e32 v48, s40, v48
	v_mul_f32_e32 v49, s40, v49
	v_mul_f32_e32 v50, s40, v50
	v_mul_f32_e32 v51, s40, v51
	v_fmac_f32_e32 v10, s56, v48
	v_fmac_f32_e32 v11, s56, v49
	v_fmac_f32_e32 v12, s56, v50
	v_fmac_f32_e32 v13, s56, v51
	v_fmac_f32_e32 v20, s60, v48
	v_fmac_f32_e32 v21, s60, v49
	v_fmac_f32_e32 v14, s60, v50
	v_fmac_f32_e32 v15, s60, v51
	v_fmac_f32_e32 v22, s92, v48
	v_fmac_f32_e32 v23, s92, v49
	v_fmac_f32_e32 v16, s92, v50
	v_fmac_f32_e32 v17, s92, v51
	v_fmac_f32_e32 v24, s96, v48
	v_fmac_f32_e32 v25, s96, v49
	v_fmac_f32_e32 v18, s96, v50
	v_fmac_f32_e32 v19, s96, v51
	v_mul_f32_e32 v52, s41, v52
	v_mul_f32_e32 v53, s41, v53
	v_mul_f32_e32 v54, s41, v54
	v_mul_f32_e32 v55, s41, v55
	v_fmac_f32_e32 v10, s57, v52
	v_fmac_f32_e32 v11, s57, v53
	v_fmac_f32_e32 v12, s57, v54
	v_fmac_f32_e32 v13, s57, v55
	v_fmac_f32_e32 v20, s61, v52
	v_fmac_f32_e32 v21, s61, v53
	v_fmac_f32_e32 v14, s61, v54
	v_fmac_f32_e32 v15, s61, v55
	v_fmac_f32_e32 v22, s93, v52
	v_fmac_f32_e32 v23, s93, v53
	v_fmac_f32_e32 v16, s93, v54
	v_fmac_f32_e32 v17, s93, v55
	v_fmac_f32_e32 v24, s97, v52
	v_fmac_f32_e32 v25, s97, v53
	v_fmac_f32_e32 v18, s97, v54
	v_fmac_f32_e32 v19, s97, v55
	v_mul_f32_e32 v56, s42, v56
	v_mul_f32_e32 v57, s42, v57
	v_mul_f32_e32 v58, s42, v58
	v_mul_f32_e32 v59, s42, v59
	v_fmac_f32_e32 v10, s58, v56
	v_fmac_f32_e32 v11, s58, v57
	v_fmac_f32_e32 v12, s58, v58
	v_fmac_f32_e32 v13, s58, v59
	v_fmac_f32_e32 v20, s62, v56
	v_fmac_f32_e32 v21, s62, v57
	v_fmac_f32_e32 v14, s62, v58
	v_fmac_f32_e32 v15, s62, v59
	v_fmac_f32_e32 v22, s94, v56
	v_fmac_f32_e32 v23, s94, v57
	v_fmac_f32_e32 v16, s94, v58
	v_fmac_f32_e32 v17, s94, v59
	v_fmac_f32_e32 v24, s98, v56
	v_fmac_f32_e32 v25, s98, v57
	v_fmac_f32_e32 v18, s98, v58
	v_fmac_f32_e32 v19, s98, v59
	v_mul_f32_e32 v60, s43, v60
	v_mul_f32_e32 v61, s43, v61
	v_mul_f32_e32 v62, s43, v62
	v_mul_f32_e32 v63, s43, v63
	v_fmac_f32_e32 v10, s59, v60
	v_fmac_f32_e32 v11, s59, v61
	v_fmac_f32_e32 v12, s59, v62
	v_fmac_f32_e32 v13, s59, v63
	v_fmac_f32_e32 v20, s63, v60
	v_fmac_f32_e32 v21, s63, v61
	v_fmac_f32_e32 v14, s63, v62
	v_fmac_f32_e32 v15, s63, v63
	v_fmac_f32_e32 v22, s95, v60
	v_fmac_f32_e32 v23, s95, v61
	v_fmac_f32_e32 v16, s95, v62
	v_fmac_f32_e32 v17, s95, v63
	v_fmac_f32_e32 v24, s99, v60
	v_fmac_f32_e32 v25, s99, v61
	v_fmac_f32_e32 v18, s99, v62
	v_fmac_f32_e32 v19, s99, v63
	s_waitcnt lgkmcnt(0)
	s_load_dwordx4 s[40:43], s[32:33], 0x30
	s_load_dwordx4 s[56:59], s[0:1], 0x30
	s_load_dwordx4 s[60:63], s[0:1], 0x230
	s_load_dwordx4 s[92:95], s[0:1], 0x430
	s_load_dwordx4 s[96:99], s[0:1], 0x630
	global_load_dwordx4 v[48:51], v1, s[50:51] offset:-4096
	global_load_dwordx4 v[52:55], v1, s[50:51]
	s_add_u32 s50, s50, 0x2000
	s_addc_u32 s51, s51, 0
	global_load_dwordx4 v[56:59], v1, s[50:51] offset:-4096
	global_load_dwordx4 v[60:63], v1, s[50:51]
	s_add_u32 s50, s50, 0x2000
	s_addc_u32 s51, s51, 0
	s_waitcnt vmcnt(24)
	v_mul_f32_e32 v64, s4, v64
	v_mul_f32_e32 v65, s4, v65
	v_mul_f32_e32 v66, s4, v66
	v_mul_f32_e32 v67, s4, v67
	v_fmac_f32_e32 v10, s12, v64
	v_fmac_f32_e32 v11, s12, v65
	v_fmac_f32_e32 v12, s12, v66
	v_fmac_f32_e32 v13, s12, v67
	v_fmac_f32_e32 v20, s16, v64
	v_fmac_f32_e32 v21, s16, v65
	v_fmac_f32_e32 v14, s16, v66
	v_fmac_f32_e32 v15, s16, v67
	v_fmac_f32_e32 v22, s36, v64
	v_fmac_f32_e32 v23, s36, v65
	v_fmac_f32_e32 v16, s36, v66
	v_fmac_f32_e32 v17, s36, v67
	v_fmac_f32_e32 v24, s64, v64
	v_fmac_f32_e32 v25, s64, v65
	v_fmac_f32_e32 v18, s64, v66
	v_fmac_f32_e32 v19, s64, v67
	v_mul_f32_e32 v68, s5, v68
	v_mul_f32_e32 v69, s5, v69
	v_mul_f32_e32 v70, s5, v70
	v_mul_f32_e32 v71, s5, v71
	v_fmac_f32_e32 v10, s13, v68
	v_fmac_f32_e32 v11, s13, v69
	v_fmac_f32_e32 v12, s13, v70
	v_fmac_f32_e32 v13, s13, v71
	v_fmac_f32_e32 v20, s17, v68
	v_fmac_f32_e32 v21, s17, v69
	v_fmac_f32_e32 v14, s17, v70
	v_fmac_f32_e32 v15, s17, v71
	v_fmac_f32_e32 v22, s37, v68
	v_fmac_f32_e32 v23, s37, v69
	v_fmac_f32_e32 v16, s37, v70
	v_fmac_f32_e32 v17, s37, v71
	v_fmac_f32_e32 v24, s65, v68
	v_fmac_f32_e32 v25, s65, v69
	v_fmac_f32_e32 v18, s65, v70
	v_fmac_f32_e32 v19, s65, v71
	v_mul_f32_e32 v72, s6, v72
	v_mul_f32_e32 v73, s6, v73
	v_mul_f32_e32 v74, s6, v74
	v_mul_f32_e32 v75, s6, v75
	v_fmac_f32_e32 v10, s14, v72
	v_fmac_f32_e32 v11, s14, v73
	v_fmac_f32_e32 v12, s14, v74
	v_fmac_f32_e32 v13, s14, v75
	v_fmac_f32_e32 v20, s18, v72
	v_fmac_f32_e32 v21, s18, v73
	v_fmac_f32_e32 v14, s18, v74
	v_fmac_f32_e32 v15, s18, v75
	v_fmac_f32_e32 v22, s38, v72
	v_fmac_f32_e32 v23, s38, v73
	v_fmac_f32_e32 v16, s38, v74
	v_fmac_f32_e32 v17, s38, v75
	v_fmac_f32_e32 v24, s66, v72
	v_fmac_f32_e32 v25, s66, v73
	v_fmac_f32_e32 v18, s66, v74
	v_fmac_f32_e32 v19, s66, v75
	v_mul_f32_e32 v76, s7, v76
	v_mul_f32_e32 v77, s7, v77
	v_mul_f32_e32 v78, s7, v78
	v_mul_f32_e32 v79, s7, v79
	v_fmac_f32_e32 v10, s15, v76
	v_fmac_f32_e32 v11, s15, v77
	v_fmac_f32_e32 v12, s15, v78
	v_fmac_f32_e32 v13, s15, v79
	v_fmac_f32_e32 v20, s19, v76
	v_fmac_f32_e32 v21, s19, v77
	v_fmac_f32_e32 v14, s19, v78
	v_fmac_f32_e32 v15, s19, v79
	v_fmac_f32_e32 v22, s39, v76
	v_fmac_f32_e32 v23, s39, v77
	v_fmac_f32_e32 v16, s39, v78
	v_fmac_f32_e32 v17, s39, v79
	v_fmac_f32_e32 v24, s67, v76
	v_fmac_f32_e32 v25, s67, v77
	v_fmac_f32_e32 v18, s67, v78
	v_fmac_f32_e32 v19, s67, v79
	s_waitcnt lgkmcnt(0)
; __global__ void __launch_bounds__(512, 2) fwd_kernel(Args a) {
;     ...
;             for (int d = 0; d < 128; ++d) {
;                 const f32x4 wv = *(const f32x4*)(wo + (size_t)d * D) * sc[d];
;                 s0 += wv * pw[d]; s1 += wv * pw[128 + d]; s2 += wv * pw[256 + d]; s3 += wv * pw[384 + d];
;             }
	s_load_dwordx4 s[4:7], s[32:33], 0x40
	s_load_dwordx4 s[12:15], s[0:1], 0x40
	s_load_dwordx4 s[16:19], s[0:1], 0x240
	s_load_dwordx4 s[36:39], s[0:1], 0x440
	s_load_dwordx4 s[64:67], s[0:1], 0x640
	global_load_dwordx4 v[64:67], v1, s[50:51] offset:-4096
	global_load_dwordx4 v[68:71], v1, s[50:51]
	s_add_u32 s50, s50, 0x2000
	s_addc_u32 s51, s51, 0
	global_load_dwordx4 v[72:75], v1, s[50:51] offset:-4096
	global_load_dwordx4 v[76:79], v1, s[50:51]
	s_add_u32 s50, s50, 0x2000
	s_addc_u32 s51, s51, 0
	s_waitcnt vmcnt(24)
	v_mul_f32_e32 v80, s40, v80
	v_mul_f32_e32 v81, s40, v81
	v_mul_f32_e32 v82, s40, v82
	v_mul_f32_e32 v83, s40, v83
	v_fmac_f32_e32 v10, s56, v80
	v_fmac_f32_e32 v11, s56, v81
	v_fmac_f32_e32 v12, s56, v82
	v_fmac_f32_e32 v13, s56, v83
	v_fmac_f32_e32 v20, s60, v80
	v_fmac_f32_e32 v21, s60, v81
	v_fmac_f32_e32 v14, s60, v82
	v_fmac_f32_e32 v15, s60, v83
	v_fmac_f32_e32 v22, s92, v80
	v_fmac_f32_e32 v23, s92, v81
	v_fmac_f32_e32 v16, s92, v82
	v_fmac_f32_e32 v17, s92, v83
	v_fmac_f32_e32 v24, s96, v80
	v_fmac_f32_e32 v25, s96, v81
	v_fmac_f32_e32 v18, s96, v82
	v_fmac_f32_e32 v19, s96, v83
	v_mul_f32_e32 v84, s41, v84
	v_mul_f32_e32 v85, s41, v85
	v_mul_f32_e32 v86, s41, v86
	v_mul_f32_e32 v87, s41, v87
	v_fmac_f32_e32 v10, s57, v84
	v_fmac_f32_e32 v11, s57, v85
	v_fmac_f32_e32 v12, s57, v86
	v_fmac_f32_e32 v13, s57, v87
	v_fmac_f32_e32 v20, s61, v84
	v_fmac_f32_e32 v21, s61, v85
	v_fmac_f32_e32 v14, s61, v86
	v_fmac_f32_e32 v15, s61, v87
	v_fmac_f32_e32 v22, s93, v84
	v_fmac_f32_e32 v23, s93, v85
	v_fmac_f32_e32 v16, s93, v86
	v_fmac_f32_e32 v17, s93, v87
	v_fmac_f32_e32 v24, s97, v84
	v_fmac_f32_e32 v25, s97, v85
	v_fmac_f32_e32 v18, s97, v86
	v_fmac_f32_e32 v19, s97, v87
	v_mul_f32_e32 v88, s42, v88
	v_mul_f32_e32 v89, s42, v89
	v_mul_f32_e32 v90, s42, v90
	v_mul_f32_e32 v91, s42, v91
	v_fmac_f32_e32 v10, s58, v88
	v_fmac_f32_e32 v11, s58, v89
	v_fmac_f32_e32 v12, s58, v90
	v_fmac_f32_e32 v13, s58, v91
	v_fmac_f32_e32 v20, s62, v88
	v_fmac_f32_e32 v21, s62, v89
	v_fmac_f32_e32 v14, s62, v90
	v_fmac_f32_e32 v15, s62, v91
	v_fmac_f32_e32 v22, s94, v88
	v_fmac_f32_e32 v23, s94, v89
	v_fmac_f32_e32 v16, s94, v90
	v_fmac_f32_e32 v17, s94, v91
	v_fmac_f32_e32 v24, s98, v88
	v_fmac_f32_e32 v25, s98, v89
	v_fmac_f32_e32 v18, s98, v90
	v_fmac_f32_e32 v19, s98, v91
	v_mul_f32_e32 v92, s43, v92
	v_mul_f32_e32 v93, s43, v93
	v_mul_f32_e32 v94, s43, v94
	v_mul_f32_e32 v95, s43, v95
	v_fmac_f32_e32 v10, s59, v92
	v_fmac_f32_e32 v11, s59, v93
	v_fmac_f32_e32 v12, s59, v94
	v_fmac_f32_e32 v13, s59, v95
	v_fmac_f32_e32 v20, s63, v92
	v_fmac_f32_e32 v21, s63, v93
	v_fmac_f32_e32 v14, s63, v94
	v_fmac_f32_e32 v15, s63, v95
	v_fmac_f32_e32 v22, s95, v92
	v_fmac_f32_e32 v23, s95, v93
	v_fmac_f32_e32 v16, s95, v94
	v_fmac_f32_e32 v17, s95, v95
	v_fmac_f32_e32 v24, s99, v92
	v_fmac_f32_e32 v25, s99, v93
	v_fmac_f32_e32 v18, s99, v94
	v_fmac_f32_e32 v19, s99, v95
	s_waitcnt lgkmcnt(0)
	s_load_dwordx4 s[40:43], s[32:33], 0x50
	s_load_dwordx4 s[56:59], s[0:1], 0x50
	s_load_dwordx4 s[60:63], s[0:1], 0x250
	s_load_dwordx4 s[92:95], s[0:1], 0x450
	s_load_dwordx4 s[96:99], s[0:1], 0x650
	global_load_dwordx4 v[80:83], v1, s[50:51] offset:-4096
	global_load_dwordx4 v[84:87], v1, s[50:51]
	s_add_u32 s50, s50, 0x2000
	s_addc_u32 s51, s51, 0
	global_load_dwordx4 v[88:91], v1, s[50:51] offset:-4096
	global_load_dwordx4 v[92:95], v1, s[50:51]
	s_add_u32 s50, s50, 0x2000
	s_addc_u32 s51, s51, 0
	s_waitcnt vmcnt(24)
	v_mul_f32_e32 v96, s4, v96
	v_mul_f32_e32 v97, s4, v97
	v_mul_f32_e32 v98, s4, v98
	v_mul_f32_e32 v99, s4, v99
	v_fmac_f32_e32 v10, s12, v96
	v_fmac_f32_e32 v11, s12, v97
	v_fmac_f32_e32 v12, s12, v98
	v_fmac_f32_e32 v13, s12, v99
	v_fmac_f32_e32 v20, s16, v96
	v_fmac_f32_e32 v21, s16, v97
	v_fmac_f32_e32 v14, s16, v98
	v_fmac_f32_e32 v15, s16, v99
	v_fmac_f32_e32 v22, s36, v96
	v_fmac_f32_e32 v23, s36, v97
	v_fmac_f32_e32 v16, s36, v98
	v_fmac_f32_e32 v17, s36, v99
	v_fmac_f32_e32 v24, s64, v96
	v_fmac_f32_e32 v25, s64, v97
	v_fmac_f32_e32 v18, s64, v98
	v_fmac_f32_e32 v19, s64, v99
	v_mul_f32_e32 v100, s5, v100
	v_mul_f32_e32 v101, s5, v101
	v_mul_f32_e32 v102, s5, v102
	v_mul_f32_e32 v103, s5, v103
	v_fmac_f32_e32 v10, s13, v100
	v_fmac_f32_e32 v11, s13, v101
	v_fmac_f32_e32 v12, s13, v102
	v_fmac_f32_e32 v13, s13, v103
	v_fmac_f32_e32 v20, s17, v100
	v_fmac_f32_e32 v21, s17, v101
	v_fmac_f32_e32 v14, s17, v102
	v_fmac_f32_e32 v15, s17, v103
	v_fmac_f32_e32 v22, s37, v100
	v_fmac_f32_e32 v23, s37, v101
	v_fmac_f32_e32 v16, s37, v102
	v_fmac_f32_e32 v17, s37, v103
	v_fmac_f32_e32 v24, s65, v100
	v_fmac_f32_e32 v25, s65, v101
	v_fmac_f32_e32 v18, s65, v102
	v_fmac_f32_e32 v19, s65, v103
	v_mul_f32_e32 v104, s6, v104
	v_mul_f32_e32 v105, s6, v105
	v_mul_f32_e32 v106, s6, v106
	v_mul_f32_e32 v107, s6, v107
	v_fmac_f32_e32 v10, s14, v104
	v_fmac_f32_e32 v11, s14, v105
	v_fmac_f32_e32 v12, s14, v106
	v_fmac_f32_e32 v13, s14, v107
	v_fmac_f32_e32 v20, s18, v104
	v_fmac_f32_e32 v21, s18, v105
	v_fmac_f32_e32 v14, s18, v106
	v_fmac_f32_e32 v15, s18, v107
	v_fmac_f32_e32 v22, s38, v104
	v_fmac_f32_e32 v23, s38, v105
	v_fmac_f32_e32 v16, s38, v106
	v_fmac_f32_e32 v17, s38, v107
	v_fmac_f32_e32 v24, s66, v104
	v_fmac_f32_e32 v25, s66, v105
	v_fmac_f32_e32 v18, s66, v106
	v_fmac_f32_e32 v19, s66, v107
	v_mul_f32_e32 v108, s7, v108
	v_mul_f32_e32 v109, s7, v109
	v_mul_f32_e32 v110, s7, v110
	v_mul_f32_e32 v111, s7, v111
	v_fmac_f32_e32 v10, s15, v108
	v_fmac_f32_e32 v11, s15, v109
	v_fmac_f32_e32 v12, s15, v110
	v_fmac_f32_e32 v13, s15, v111
	v_fmac_f32_e32 v20, s19, v108
	v_fmac_f32_e32 v21, s19, v109
	v_fmac_f32_e32 v14, s19, v110
	v_fmac_f32_e32 v15, s19, v111
	v_fmac_f32_e32 v22, s39, v108
	v_fmac_f32_e32 v23, s39, v109
	v_fmac_f32_e32 v16, s39, v110
	v_fmac_f32_e32 v17, s39, v111
	v_fmac_f32_e32 v24, s67, v108
	v_fmac_f32_e32 v25, s67, v109
	v_fmac_f32_e32 v18, s67, v110
	v_fmac_f32_e32 v19, s67, v111
	s_waitcnt lgkmcnt(0)
; __global__ void __launch_bounds__(512, 2) fwd_kernel(Args a) {
;     ...
;             for (int d = 0; d < 128; ++d) {
;                 const f32x4 wv = *(const f32x4*)(wo + (size_t)d * D) * sc[d];
;                 s0 += wv * pw[d]; s1 += wv * pw[128 + d]; s2 += wv * pw[256 + d]; s3 += wv * pw[384 + d];
;             }
	s_load_dwordx4 s[4:7], s[32:33], 0x60
	s_load_dwordx4 s[12:15], s[0:1], 0x60
	s_load_dwordx4 s[16:19], s[0:1], 0x260
	s_load_dwordx4 s[36:39], s[0:1], 0x460
	s_load_dwordx4 s[64:67], s[0:1], 0x660
	global_load_dwordx4 v[96:99], v1, s[50:51] offset:-4096
	global_load_dwordx4 v[100:103], v1, s[50:51]
	s_add_u32 s50, s50, 0x2000
	s_addc_u32 s51, s51, 0
	global_load_dwordx4 v[104:107], v1, s[50:51] offset:-4096
	global_load_dwordx4 v[108:111], v1, s[50:51]
	s_add_u32 s50, s50, 0x2000
	s_addc_u32 s51, s51, 0
	s_waitcnt vmcnt(24)
	v_mul_f32_e32 v112, s40, v112
	v_mul_f32_e32 v113, s40, v113
	v_mul_f32_e32 v114, s40, v114
	v_mul_f32_e32 v115, s40, v115
	v_fmac_f32_e32 v10, s56, v112
	v_fmac_f32_e32 v11, s56, v113
	v_fmac_f32_e32 v12, s56, v114
	v_fmac_f32_e32 v13, s56, v115
	v_fmac_f32_e32 v20, s60, v112
	v_fmac_f32_e32 v21, s60, v113
	v_fmac_f32_e32 v14, s60, v114
	v_fmac_f32_e32 v15, s60, v115
	v_fmac_f32_e32 v22, s92, v112
	v_fmac_f32_e32 v23, s92, v113
	v_fmac_f32_e32 v16, s92, v114
	v_fmac_f32_e32 v17, s92, v115
	v_fmac_f32_e32 v24, s96, v112
	v_fmac_f32_e32 v25, s96, v113
	v_fmac_f32_e32 v18, s96, v114
	v_fmac_f32_e32 v19, s96, v115
	v_mul_f32_e32 v116, s41, v116
	v_mul_f32_e32 v117, s41, v117
	v_mul_f32_e32 v118, s41, v118
	v_mul_f32_e32 v119, s41, v119
	v_fmac_f32_e32 v10, s57, v116
	v_fmac_f32_e32 v11, s57, v117
	v_fmac_f32_e32 v12, s57, v118
	v_fmac_f32_e32 v13, s57, v119
	v_fmac_f32_e32 v20, s61, v116
	v_fmac_f32_e32 v21, s61, v117
	v_fmac_f32_e32 v14, s61, v118
	v_fmac_f32_e32 v15, s61, v119
	v_fmac_f32_e32 v22, s93, v116
	v_fmac_f32_e32 v23, s93, v117
	v_fmac_f32_e32 v16, s93, v118
	v_fmac_f32_e32 v17, s93, v119
	v_fmac_f32_e32 v24, s97, v116
	v_fmac_f32_e32 v25, s97, v117
	v_fmac_f32_e32 v18, s97, v118
	v_fmac_f32_e32 v19, s97, v119
	v_mul_f32_e32 v120, s42, v120
	v_mul_f32_e32 v121, s42, v121
	v_mul_f32_e32 v122, s42, v122
	v_mul_f32_e32 v123, s42, v123
	v_fmac_f32_e32 v10, s58, v120
	v_fmac_f32_e32 v11, s58, v121
	v_fmac_f32_e32 v12, s58, v122
	v_fmac_f32_e32 v13, s58, v123
	v_fmac_f32_e32 v20, s62, v120
	v_fmac_f32_e32 v21, s62, v121
	v_fmac_f32_e32 v14, s62, v122
	v_fmac_f32_e32 v15, s62, v123
	v_fmac_f32_e32 v22, s94, v120
	v_fmac_f32_e32 v23, s94, v121
	v_fmac_f32_e32 v16, s94, v122
	v_fmac_f32_e32 v17, s94, v123
	v_fmac_f32_e32 v24, s98, v120
	v_fmac_f32_e32 v25, s98, v121
	v_fmac_f32_e32 v18, s98, v122
	v_fmac_f32_e32 v19, s98, v123
	v_mul_f32_e32 v124, s43, v124
	v_mul_f32_e32 v125, s43, v125
	v_mul_f32_e32 v126, s43, v126
	v_mul_f32_e32 v127, s43, v127
	v_fmac_f32_e32 v10, s59, v124
	v_fmac_f32_e32 v11, s59, v125
	v_fmac_f32_e32 v12, s59, v126
	v_fmac_f32_e32 v13, s59, v127
	v_fmac_f32_e32 v20, s63, v124
	v_fmac_f32_e32 v21, s63, v125
	v_fmac_f32_e32 v14, s63, v126
	v_fmac_f32_e32 v15, s63, v127
	v_fmac_f32_e32 v22, s95, v124
	v_fmac_f32_e32 v23, s95, v125
	v_fmac_f32_e32 v16, s95, v126
	v_fmac_f32_e32 v17, s95, v127
	v_fmac_f32_e32 v24, s99, v124
	v_fmac_f32_e32 v25, s99, v125
	v_fmac_f32_e32 v18, s99, v126
	v_fmac_f32_e32 v19, s99, v127
	s_waitcnt lgkmcnt(0)
	s_load_dwordx4 s[40:43], s[32:33], 0x70
	s_load_dwordx4 s[56:59], s[0:1], 0x70
	s_load_dwordx4 s[60:63], s[0:1], 0x270
	s_load_dwordx4 s[92:95], s[0:1], 0x470
	s_load_dwordx4 s[96:99], s[0:1], 0x670
	global_load_dwordx4 v[112:115], v1, s[50:51] offset:-4096
	global_load_dwordx4 v[116:119], v1, s[50:51]
	s_add_u32 s50, s50, 0x2000
	s_addc_u32 s51, s51, 0
	global_load_dwordx4 v[120:123], v1, s[50:51] offset:-4096
	global_load_dwordx4 v[124:127], v1, s[50:51]
	s_add_u32 s50, s50, 0x2000
	s_addc_u32 s51, s51, 0
	s_waitcnt vmcnt(24)
	v_mul_f32_e32 v128, s4, v128
	v_mul_f32_e32 v129, s4, v129
	v_mul_f32_e32 v130, s4, v130
	v_mul_f32_e32 v131, s4, v131
	v_fmac_f32_e32 v10, s12, v128
	v_fmac_f32_e32 v11, s12, v129
	v_fmac_f32_e32 v12, s12, v130
	v_fmac_f32_e32 v13, s12, v131
	v_fmac_f32_e32 v20, s16, v128
	v_fmac_f32_e32 v21, s16, v129
	v_fmac_f32_e32 v14, s16, v130
	v_fmac_f32_e32 v15, s16, v131
	v_fmac_f32_e32 v22, s36, v128
	v_fmac_f32_e32 v23, s36, v129
	v_fmac_f32_e32 v16, s36, v130
	v_fmac_f32_e32 v17, s36, v131
	v_fmac_f32_e32 v24, s64, v128
	v_fmac_f32_e32 v25, s64, v129
	v_fmac_f32_e32 v18, s64, v130
	v_fmac_f32_e32 v19, s64, v131
	v_mul_f32_e32 v132, s5, v132
	v_mul_f32_e32 v133, s5, v133
	v_mul_f32_e32 v134, s5, v134
	v_mul_f32_e32 v135, s5, v135
	v_fmac_f32_e32 v10, s13, v132
	v_fmac_f32_e32 v11, s13, v133
	v_fmac_f32_e32 v12, s13, v134
	v_fmac_f32_e32 v13, s13, v135
	v_fmac_f32_e32 v20, s17, v132
	v_fmac_f32_e32 v21, s17, v133
	v_fmac_f32_e32 v14, s17, v134
	v_fmac_f32_e32 v15, s17, v135
	v_fmac_f32_e32 v22, s37, v132
	v_fmac_f32_e32 v23, s37, v133
	v_fmac_f32_e32 v16, s37, v134
	v_fmac_f32_e32 v17, s37, v135
	v_fmac_f32_e32 v24, s65, v132
	v_fmac_f32_e32 v25, s65, v133
	v_fmac_f32_e32 v18, s65, v134
	v_fmac_f32_e32 v19, s65, v135
	v_mul_f32_e32 v136, s6, v136
	v_mul_f32_e32 v137, s6, v137
	v_mul_f32_e32 v138, s6, v138
	v_mul_f32_e32 v139, s6, v139
	v_fmac_f32_e32 v10, s14, v136
	v_fmac_f32_e32 v11, s14, v137
	v_fmac_f32_e32 v12, s14, v138
	v_fmac_f32_e32 v13, s14, v139
	v_fmac_f32_e32 v20, s18, v136
	v_fmac_f32_e32 v21, s18, v137
	v_fmac_f32_e32 v14, s18, v138
	v_fmac_f32_e32 v15, s18, v139
	v_fmac_f32_e32 v22, s38, v136
	v_fmac_f32_e32 v23, s38, v137
	v_fmac_f32_e32 v16, s38, v138
	v_fmac_f32_e32 v17, s38, v139
	v_fmac_f32_e32 v24, s66, v136
	v_fmac_f32_e32 v25, s66, v137
	v_fmac_f32_e32 v18, s66, v138
	v_fmac_f32_e32 v19, s66, v139
	v_mul_f32_e32 v140, s7, v140
	v_mul_f32_e32 v141, s7, v141
	v_mul_f32_e32 v142, s7, v142
	v_mul_f32_e32 v143, s7, v143
	v_fmac_f32_e32 v10, s15, v140
	v_fmac_f32_e32 v11, s15, v141
	v_fmac_f32_e32 v12, s15, v142
	v_fmac_f32_e32 v13, s15, v143
	v_fmac_f32_e32 v20, s19, v140
	v_fmac_f32_e32 v21, s19, v141
	v_fmac_f32_e32 v14, s19, v142
	v_fmac_f32_e32 v15, s19, v143
	v_fmac_f32_e32 v22, s39, v140
	v_fmac_f32_e32 v23, s39, v141
	v_fmac_f32_e32 v16, s39, v142
	v_fmac_f32_e32 v17, s39, v143
	v_fmac_f32_e32 v24, s67, v140
	v_fmac_f32_e32 v25, s67, v141
	v_fmac_f32_e32 v18, s67, v142
	v_fmac_f32_e32 v19, s67, v143
	s_waitcnt lgkmcnt(0)
; __global__ void __launch_bounds__(512, 2) fwd_kernel(Args a) {
;     ...
;             for (int d = 0; d < 128; ++d) {
;                 const f32x4 wv = *(const f32x4*)(wo + (size_t)d * D) * sc[d];
;                 s0 += wv * pw[d]; s1 += wv * pw[128 + d]; s2 += wv * pw[256 + d]; s3 += wv * pw[384 + d];
;             }
	s_load_dwordx4 s[4:7], s[32:33], 0x80
	s_load_dwordx4 s[12:15], s[0:1], 0x80
	s_load_dwordx4 s[16:19], s[0:1], 0x280
	s_load_dwordx4 s[36:39], s[0:1], 0x480
	s_load_dwordx4 s[64:67], s[0:1], 0x680
	global_load_dwordx4 v[128:131], v1, s[50:51] offset:-4096
	global_load_dwordx4 v[132:135], v1, s[50:51]
	s_add_u32 s50, s50, 0x2000
	s_addc_u32 s51, s51, 0
	global_load_dwordx4 v[136:139], v1, s[50:51] offset:-4096
	global_load_dwordx4 v[140:143], v1, s[50:51]
	s_add_u32 s50, s50, 0x2000
	s_addc_u32 s51, s51, 0
	s_waitcnt vmcnt(24)
	v_mul_f32_e32 v32, s40, v32
	v_mul_f32_e32 v33, s40, v33
	v_mul_f32_e32 v34, s40, v34
	v_mul_f32_e32 v35, s40, v35
	v_fmac_f32_e32 v10, s56, v32
	v_fmac_f32_e32 v11, s56, v33
	v_fmac_f32_e32 v12, s56, v34
	v_fmac_f32_e32 v13, s56, v35
	v_fmac_f32_e32 v20, s60, v32
	v_fmac_f32_e32 v21, s60, v33
	v_fmac_f32_e32 v14, s60, v34
	v_fmac_f32_e32 v15, s60, v35
	v_fmac_f32_e32 v22, s92, v32
	v_fmac_f32_e32 v23, s92, v33
	v_fmac_f32_e32 v16, s92, v34
	v_fmac_f32_e32 v17, s92, v35
	v_fmac_f32_e32 v24, s96, v32
	v_fmac_f32_e32 v25, s96, v33
	v_fmac_f32_e32 v18, s96, v34
	v_fmac_f32_e32 v19, s96, v35
	v_mul_f32_e32 v36, s41, v36
	v_mul_f32_e32 v37, s41, v37
	v_mul_f32_e32 v38, s41, v38
	v_mul_f32_e32 v39, s41, v39
	v_fmac_f32_e32 v10, s57, v36
	v_fmac_f32_e32 v11, s57, v37
	v_fmac_f32_e32 v12, s57, v38
	v_fmac_f32_e32 v13, s57, v39
	v_fmac_f32_e32 v20, s61, v36
	v_fmac_f32_e32 v21, s61, v37
	v_fmac_f32_e32 v14, s61, v38
	v_fmac_f32_e32 v15, s61, v39
	v_fmac_f32_e32 v22, s93, v36
	v_fmac_f32_e32 v23, s93, v37
	v_fmac_f32_e32 v16, s93, v38
	v_fmac_f32_e32 v17, s93, v39
	v_fmac_f32_e32 v24, s97, v36
	v_fmac_f32_e32 v25, s97, v37
	v_fmac_f32_e32 v18, s97, v38
	v_fmac_f32_e32 v19, s97, v39
	v_mul_f32_e32 v40, s42, v40
	v_mul_f32_e32 v41, s42, v41
	v_mul_f32_e32 v42, s42, v42
	v_mul_f32_e32 v43, s42, v43
	v_fmac_f32_e32 v10, s58, v40
	v_fmac_f32_e32 v11, s58, v41
	v_fmac_f32_e32 v12, s58, v42
	v_fmac_f32_e32 v13, s58, v43
	v_fmac_f32_e32 v20, s62, v40
	v_fmac_f32_e32 v21, s62, v41
	v_fmac_f32_e32 v14, s62, v42
	v_fmac_f32_e32 v15, s62, v43
	v_fmac_f32_e32 v22, s94, v40
	v_fmac_f32_e32 v23, s94, v41
	v_fmac_f32_e32 v16, s94, v42
	v_fmac_f32_e32 v17, s94, v43
	v_fmac_f32_e32 v24, s98, v40
	v_fmac_f32_e32 v25, s98, v41
	v_fmac_f32_e32 v18, s98, v42
	v_fmac_f32_e32 v19, s98, v43
	v_mul_f32_e32 v44, s43, v44
	v_mul_f32_e32 v45, s43, v45
	v_mul_f32_e32 v46, s43, v46
	v_mul_f32_e32 v47, s43, v47
	v_fmac_f32_e32 v10, s59, v44
	v_fmac_f32_e32 v11, s59, v45
	v_fmac_f32_e32 v12, s59, v46
	v_fmac_f32_e32 v13, s59, v47
	v_fmac_f32_e32 v20, s63, v44
	v_fmac_f32_e32 v21, s63, v45
	v_fmac_f32_e32 v14, s63, v46
	v_fmac_f32_e32 v15, s63, v47
	v_fmac_f32_e32 v22, s95, v44
	v_fmac_f32_e32 v23, s95, v45
	v_fmac_f32_e32 v16, s95, v46
	v_fmac_f32_e32 v17, s95, v47
	v_fmac_f32_e32 v24, s99, v44
	v_fmac_f32_e32 v25, s99, v45
	v_fmac_f32_e32 v18, s99, v46
	v_fmac_f32_e32 v19, s99, v47
	s_waitcnt lgkmcnt(0)
	s_load_dwordx4 s[40:43], s[32:33], 0x90
	s_load_dwordx4 s[56:59], s[0:1], 0x90
	s_load_dwordx4 s[60:63], s[0:1], 0x290
	s_load_dwordx4 s[92:95], s[0:1], 0x490
	s_load_dwordx4 s[96:99], s[0:1], 0x690
	global_load_dwordx4 v[32:35], v1, s[50:51] offset:-4096
	global_load_dwordx4 v[36:39], v1, s[50:51]
	s_add_u32 s50, s50, 0x2000
	s_addc_u32 s51, s51, 0
	global_load_dwordx4 v[40:43], v1, s[50:51] offset:-4096
	global_load_dwordx4 v[44:47], v1, s[50:51]
	s_add_u32 s50, s50, 0x2000
	s_addc_u32 s51, s51, 0
	s_waitcnt vmcnt(24)
	v_mul_f32_e32 v48, s4, v48
	v_mul_f32_e32 v49, s4, v49
	v_mul_f32_e32 v50, s4, v50
	v_mul_f32_e32 v51, s4, v51
	v_fmac_f32_e32 v10, s12, v48
	v_fmac_f32_e32 v11, s12, v49
	v_fmac_f32_e32 v12, s12, v50
	v_fmac_f32_e32 v13, s12, v51
	v_fmac_f32_e32 v20, s16, v48
	v_fmac_f32_e32 v21, s16, v49
	v_fmac_f32_e32 v14, s16, v50
	v_fmac_f32_e32 v15, s16, v51
	v_fmac_f32_e32 v22, s36, v48
	v_fmac_f32_e32 v23, s36, v49
	v_fmac_f32_e32 v16, s36, v50
	v_fmac_f32_e32 v17, s36, v51
	v_fmac_f32_e32 v24, s64, v48
	v_fmac_f32_e32 v25, s64, v49
	v_fmac_f32_e32 v18, s64, v50
	v_fmac_f32_e32 v19, s64, v51
	v_mul_f32_e32 v52, s5, v52
	v_mul_f32_e32 v53, s5, v53
	v_mul_f32_e32 v54, s5, v54
	v_mul_f32_e32 v55, s5, v55
	v_fmac_f32_e32 v10, s13, v52
	v_fmac_f32_e32 v11, s13, v53
	v_fmac_f32_e32 v12, s13, v54
	v_fmac_f32_e32 v13, s13, v55
	v_fmac_f32_e32 v20, s17, v52
	v_fmac_f32_e32 v21, s17, v53
	v_fmac_f32_e32 v14, s17, v54
	v_fmac_f32_e32 v15, s17, v55
	v_fmac_f32_e32 v22, s37, v52
	v_fmac_f32_e32 v23, s37, v53
	v_fmac_f32_e32 v16, s37, v54
	v_fmac_f32_e32 v17, s37, v55
	v_fmac_f32_e32 v24, s65, v52
	v_fmac_f32_e32 v25, s65, v53
	v_fmac_f32_e32 v18, s65, v54
	v_fmac_f32_e32 v19, s65, v55
	v_mul_f32_e32 v56, s6, v56
	v_mul_f32_e32 v57, s6, v57
	v_mul_f32_e32 v58, s6, v58
	v_mul_f32_e32 v59, s6, v59
	v_fmac_f32_e32 v10, s14, v56
	v_fmac_f32_e32 v11, s14, v57
	v_fmac_f32_e32 v12, s14, v58
	v_fmac_f32_e32 v13, s14, v59
	v_fmac_f32_e32 v20, s18, v56
	v_fmac_f32_e32 v21, s18, v57
	v_fmac_f32_e32 v14, s18, v58
	v_fmac_f32_e32 v15, s18, v59
	v_fmac_f32_e32 v22, s38, v56
	v_fmac_f32_e32 v23, s38, v57
	v_fmac_f32_e32 v16, s38, v58
	v_fmac_f32_e32 v17, s38, v59
	v_fmac_f32_e32 v24, s66, v56
	v_fmac_f32_e32 v25, s66, v57
	v_fmac_f32_e32 v18, s66, v58
	v_fmac_f32_e32 v19, s66, v59
	v_mul_f32_e32 v60, s7, v60
	v_mul_f32_e32 v61, s7, v61
	v_mul_f32_e32 v62, s7, v62
	v_mul_f32_e32 v63, s7, v63
	v_fmac_f32_e32 v10, s15, v60
	v_fmac_f32_e32 v11, s15, v61
	v_fmac_f32_e32 v12, s15, v62
	v_fmac_f32_e32 v13, s15, v63
	v_fmac_f32_e32 v20, s19, v60
	v_fmac_f32_e32 v21, s19, v61
	v_fmac_f32_e32 v14, s19, v62
	v_fmac_f32_e32 v15, s19, v63
	v_fmac_f32_e32 v22, s39, v60
	v_fmac_f32_e32 v23, s39, v61
	v_fmac_f32_e32 v16, s39, v62
	v_fmac_f32_e32 v17, s39, v63
	v_fmac_f32_e32 v24, s67, v60
	v_fmac_f32_e32 v25, s67, v61
	v_fmac_f32_e32 v18, s67, v62
	v_fmac_f32_e32 v19, s67, v63
	s_waitcnt lgkmcnt(0)
; __global__ void __launch_bounds__(512, 2) fwd_kernel(Args a) {
;     ...
;             for (int d = 0; d < 128; ++d) {
;                 const f32x4 wv = *(const f32x4*)(wo + (size_t)d * D) * sc[d];
;                 s0 += wv * pw[d]; s1 += wv * pw[128 + d]; s2 += wv * pw[256 + d]; s3 += wv * pw[384 + d];
;             }
	s_load_dwordx4 s[4:7], s[32:33], 0xa0
	s_load_dwordx4 s[12:15], s[0:1], 0xa0
	s_load_dwordx4 s[16:19], s[0:1], 0x2a0
	s_load_dwordx4 s[36:39], s[0:1], 0x4a0
	s_load_dwordx4 s[64:67], s[0:1], 0x6a0
	global_load_dwordx4 v[48:51], v1, s[50:51] offset:-4096
	global_load_dwordx4 v[52:55], v1, s[50:51]
	s_add_u32 s50, s50, 0x2000
	s_addc_u32 s51, s51, 0
	global_load_dwordx4 v[56:59], v1, s[50:51] offset:-4096
	global_load_dwordx4 v[60:63], v1, s[50:51]
	s_add_u32 s50, s50, 0x2000
	s_addc_u32 s51, s51, 0
	s_waitcnt vmcnt(24)
	v_mul_f32_e32 v64, s40, v64
	v_mul_f32_e32 v65, s40, v65
	v_mul_f32_e32 v66, s40, v66
	v_mul_f32_e32 v67, s40, v67
	v_fmac_f32_e32 v10, s56, v64
	v_fmac_f32_e32 v11, s56, v65
	v_fmac_f32_e32 v12, s56, v66
	v_fmac_f32_e32 v13, s56, v67
	v_fmac_f32_e32 v20, s60, v64
	v_fmac_f32_e32 v21, s60, v65
	v_fmac_f32_e32 v14, s60, v66
	v_fmac_f32_e32 v15, s60, v67
	v_fmac_f32_e32 v22, s92, v64
	v_fmac_f32_e32 v23, s92, v65
	v_fmac_f32_e32 v16, s92, v66
	v_fmac_f32_e32 v17, s92, v67
	v_fmac_f32_e32 v24, s96, v64
	v_fmac_f32_e32 v25, s96, v65
	v_fmac_f32_e32 v18, s96, v66
	v_fmac_f32_e32 v19, s96, v67
	v_mul_f32_e32 v68, s41, v68
	v_mul_f32_e32 v69, s41, v69
	v_mul_f32_e32 v70, s41, v70
	v_mul_f32_e32 v71, s41, v71
	v_fmac_f32_e32 v10, s57, v68
	v_fmac_f32_e32 v11, s57, v69
	v_fmac_f32_e32 v12, s57, v70
	v_fmac_f32_e32 v13, s57, v71
	v_fmac_f32_e32 v20, s61, v68
	v_fmac_f32_e32 v21, s61, v69
	v_fmac_f32_e32 v14, s61, v70
	v_fmac_f32_e32 v15, s61, v71
	v_fmac_f32_e32 v22, s93, v68
	v_fmac_f32_e32 v23, s93, v69
	v_fmac_f32_e32 v16, s93, v70
	v_fmac_f32_e32 v17, s93, v71
	v_fmac_f32_e32 v24, s97, v68
	v_fmac_f32_e32 v25, s97, v69
	v_fmac_f32_e32 v18, s97, v70
	v_fmac_f32_e32 v19, s97, v71
	v_mul_f32_e32 v72, s42, v72
	v_mul_f32_e32 v73, s42, v73
	v_mul_f32_e32 v74, s42, v74
	v_mul_f32_e32 v75, s42, v75
	v_fmac_f32_e32 v10, s58, v72
	v_fmac_f32_e32 v11, s58, v73
	v_fmac_f32_e32 v12, s58, v74
	v_fmac_f32_e32 v13, s58, v75
	v_fmac_f32_e32 v20, s62, v72
	v_fmac_f32_e32 v21, s62, v73
	v_fmac_f32_e32 v14, s62, v74
	v_fmac_f32_e32 v15, s62, v75
	v_fmac_f32_e32 v22, s94, v72
	v_fmac_f32_e32 v23, s94, v73
	v_fmac_f32_e32 v16, s94, v74
	v_fmac_f32_e32 v17, s94, v75
	v_fmac_f32_e32 v24, s98, v72
	v_fmac_f32_e32 v25, s98, v73
	v_fmac_f32_e32 v18, s98, v74
	v_fmac_f32_e32 v19, s98, v75
	v_mul_f32_e32 v76, s43, v76
	v_mul_f32_e32 v77, s43, v77
	v_mul_f32_e32 v78, s43, v78
	v_mul_f32_e32 v79, s43, v79
	v_fmac_f32_e32 v10, s59, v76
	v_fmac_f32_e32 v11, s59, v77
	v_fmac_f32_e32 v12, s59, v78
	v_fmac_f32_e32 v13, s59, v79
	v_fmac_f32_e32 v20, s63, v76
	v_fmac_f32_e32 v21, s63, v77
	v_fmac_f32_e32 v14, s63, v78
	v_fmac_f32_e32 v15, s63, v79
	v_fmac_f32_e32 v22, s95, v76
	v_fmac_f32_e32 v23, s95, v77
	v_fmac_f32_e32 v16, s95, v78
	v_fmac_f32_e32 v17, s95, v79
	v_fmac_f32_e32 v24, s99, v76
	v_fmac_f32_e32 v25, s99, v77
	v_fmac_f32_e32 v18, s99, v78
	v_fmac_f32_e32 v19, s99, v79
	s_waitcnt lgkmcnt(0)
	s_load_dwordx4 s[40:43], s[32:33], 0xb0
	s_load_dwordx4 s[56:59], s[0:1], 0xb0
	s_load_dwordx4 s[60:63], s[0:1], 0x2b0
	s_load_dwordx4 s[92:95], s[0:1], 0x4b0
	s_load_dwordx4 s[96:99], s[0:1], 0x6b0
	global_load_dwordx4 v[64:67], v1, s[50:51] offset:-4096
	global_load_dwordx4 v[68:71], v1, s[50:51]
	s_add_u32 s50, s50, 0x2000
	s_addc_u32 s51, s51, 0
	global_load_dwordx4 v[72:75], v1, s[50:51] offset:-4096
	global_load_dwordx4 v[76:79], v1, s[50:51]
	s_add_u32 s50, s50, 0x2000
	s_addc_u32 s51, s51, 0
	s_waitcnt vmcnt(24)
	v_mul_f32_e32 v80, s4, v80
	v_mul_f32_e32 v81, s4, v81
	v_mul_f32_e32 v82, s4, v82
	v_mul_f32_e32 v83, s4, v83
	v_fmac_f32_e32 v10, s12, v80
	v_fmac_f32_e32 v11, s12, v81
	v_fmac_f32_e32 v12, s12, v82
	v_fmac_f32_e32 v13, s12, v83
	v_fmac_f32_e32 v20, s16, v80
	v_fmac_f32_e32 v21, s16, v81
	v_fmac_f32_e32 v14, s16, v82
	v_fmac_f32_e32 v15, s16, v83
	v_fmac_f32_e32 v22, s36, v80
	v_fmac_f32_e32 v23, s36, v81
	v_fmac_f32_e32 v16, s36, v82
	v_fmac_f32_e32 v17, s36, v83
	v_fmac_f32_e32 v24, s64, v80
	v_fmac_f32_e32 v25, s64, v81
	v_fmac_f32_e32 v18, s64, v82
	v_fmac_f32_e32 v19, s64, v83
	v_mul_f32_e32 v84, s5, v84
	v_mul_f32_e32 v85, s5, v85
	v_mul_f32_e32 v86, s5, v86
	v_mul_f32_e32 v87, s5, v87
	v_fmac_f32_e32 v10, s13, v84
	v_fmac_f32_e32 v11, s13, v85
	v_fmac_f32_e32 v12, s13, v86
	v_fmac_f32_e32 v13, s13, v87
	v_fmac_f32_e32 v20, s17, v84
	v_fmac_f32_e32 v21, s17, v85
	v_fmac_f32_e32 v14, s17, v86
	v_fmac_f32_e32 v15, s17, v87
	v_fmac_f32_e32 v22, s37, v84
	v_fmac_f32_e32 v23, s37, v85
	v_fmac_f32_e32 v16, s37, v86
	v_fmac_f32_e32 v17, s37, v87
	v_fmac_f32_e32 v24, s65, v84
	v_fmac_f32_e32 v25, s65, v85
	v_fmac_f32_e32 v18, s65, v86
	v_fmac_f32_e32 v19, s65, v87
	v_mul_f32_e32 v88, s6, v88
	v_mul_f32_e32 v89, s6, v89
	v_mul_f32_e32 v90, s6, v90
	v_mul_f32_e32 v91, s6, v91
	v_fmac_f32_e32 v10, s14, v88
	v_fmac_f32_e32 v11, s14, v89
	v_fmac_f32_e32 v12, s14, v90
	v_fmac_f32_e32 v13, s14, v91
	v_fmac_f32_e32 v20, s18, v88
	v_fmac_f32_e32 v21, s18, v89
	v_fmac_f32_e32 v14, s18, v90
	v_fmac_f32_e32 v15, s18, v91
	v_fmac_f32_e32 v22, s38, v88
	v_fmac_f32_e32 v23, s38, v89
	v_fmac_f32_e32 v16, s38, v90
	v_fmac_f32_e32 v17, s38, v91
	v_fmac_f32_e32 v24, s66, v88
	v_fmac_f32_e32 v25, s66, v89
	v_fmac_f32_e32 v18, s66, v90
	v_fmac_f32_e32 v19, s66, v91
	v_mul_f32_e32 v92, s7, v92
	v_mul_f32_e32 v93, s7, v93
	v_mul_f32_e32 v94, s7, v94
	v_mul_f32_e32 v95, s7, v95
	v_fmac_f32_e32 v10, s15, v92
	v_fmac_f32_e32 v11, s15, v93
	v_fmac_f32_e32 v12, s15, v94
	v_fmac_f32_e32 v13, s15, v95
	v_fmac_f32_e32 v20, s19, v92
	v_fmac_f32_e32 v21, s19, v93
	v_fmac_f32_e32 v14, s19, v94
	v_fmac_f32_e32 v15, s19, v95
	v_fmac_f32_e32 v22, s39, v92
	v_fmac_f32_e32 v23, s39, v93
	v_fmac_f32_e32 v16, s39, v94
	v_fmac_f32_e32 v17, s39, v95
	v_fmac_f32_e32 v24, s67, v92
	v_fmac_f32_e32 v25, s67, v93
	v_fmac_f32_e32 v18, s67, v94
	v_fmac_f32_e32 v19, s67, v95
	s_waitcnt lgkmcnt(0)
; __global__ void __launch_bounds__(512, 2) fwd_kernel(Args a) {
;     ...
;             for (int d = 0; d < 128; ++d) {
;                 const f32x4 wv = *(const f32x4*)(wo + (size_t)d * D) * sc[d];
;                 s0 += wv * pw[d]; s1 += wv * pw[128 + d]; s2 += wv * pw[256 + d]; s3 += wv * pw[384 + d];
;             }
	s_load_dwordx4 s[4:7], s[32:33], 0xc0
	s_load_dwordx4 s[12:15], s[0:1], 0xc0
	s_load_dwordx4 s[16:19], s[0:1], 0x2c0
	s_load_dwordx4 s[36:39], s[0:1], 0x4c0
	s_load_dwordx4 s[64:67], s[0:1], 0x6c0
	global_load_dwordx4 v[80:83], v1, s[50:51] offset:-4096
	global_load_dwordx4 v[84:87], v1, s[50:51]
	s_add_u32 s50, s50, 0x2000
	s_addc_u32 s51, s51, 0
	global_load_dwordx4 v[88:91], v1, s[50:51] offset:-4096
	global_load_dwordx4 v[92:95], v1, s[50:51]
	s_add_u32 s50, s50, 0x2000
	s_addc_u32 s51, s51, 0
	s_waitcnt vmcnt(24)
	v_mul_f32_e32 v96, s40, v96
	v_mul_f32_e32 v97, s40, v97
	v_mul_f32_e32 v98, s40, v98
	v_mul_f32_e32 v99, s40, v99
	v_fmac_f32_e32 v10, s56, v96
	v_fmac_f32_e32 v11, s56, v97
	v_fmac_f32_e32 v12, s56, v98
	v_fmac_f32_e32 v13, s56, v99
	v_fmac_f32_e32 v20, s60, v96
	v_fmac_f32_e32 v21, s60, v97
	v_fmac_f32_e32 v14, s60, v98
	v_fmac_f32_e32 v15, s60, v99
	v_fmac_f32_e32 v22, s92, v96
	v_fmac_f32_e32 v23, s92, v97
	v_fmac_f32_e32 v16, s92, v98
	v_fmac_f32_e32 v17, s92, v99
	v_fmac_f32_e32 v24, s96, v96
	v_fmac_f32_e32 v25, s96, v97
	v_fmac_f32_e32 v18, s96, v98
	v_fmac_f32_e32 v19, s96, v99
	v_mul_f32_e32 v100, s41, v100
	v_mul_f32_e32 v101, s41, v101
	v_mul_f32_e32 v102, s41, v102
	v_mul_f32_e32 v103, s41, v103
	v_fmac_f32_e32 v10, s57, v100
	v_fmac_f32_e32 v11, s57, v101
	v_fmac_f32_e32 v12, s57, v102
	v_fmac_f32_e32 v13, s57, v103
	v_fmac_f32_e32 v20, s61, v100
	v_fmac_f32_e32 v21, s61, v101
	v_fmac_f32_e32 v14, s61, v102
	v_fmac_f32_e32 v15, s61, v103
	v_fmac_f32_e32 v22, s93, v100
	v_fmac_f32_e32 v23, s93, v101
	v_fmac_f32_e32 v16, s93, v102
	v_fmac_f32_e32 v17, s93, v103
	v_fmac_f32_e32 v24, s97, v100
	v_fmac_f32_e32 v25, s97, v101
	v_fmac_f32_e32 v18, s97, v102
	v_fmac_f32_e32 v19, s97, v103
	v_mul_f32_e32 v104, s42, v104
	v_mul_f32_e32 v105, s42, v105
	v_mul_f32_e32 v106, s42, v106
	v_mul_f32_e32 v107, s42, v107
	v_fmac_f32_e32 v10, s58, v104
	v_fmac_f32_e32 v11, s58, v105
	v_fmac_f32_e32 v12, s58, v106
	v_fmac_f32_e32 v13, s58, v107
	v_fmac_f32_e32 v20, s62, v104
	v_fmac_f32_e32 v21, s62, v105
	v_fmac_f32_e32 v14, s62, v106
	v_fmac_f32_e32 v15, s62, v107
	v_fmac_f32_e32 v22, s94, v104
	v_fmac_f32_e32 v23, s94, v105
	v_fmac_f32_e32 v16, s94, v106
	v_fmac_f32_e32 v17, s94, v107
	v_fmac_f32_e32 v24, s98, v104
	v_fmac_f32_e32 v25, s98, v105
	v_fmac_f32_e32 v18, s98, v106
	v_fmac_f32_e32 v19, s98, v107
	v_mul_f32_e32 v108, s43, v108
	v_mul_f32_e32 v109, s43, v109
	v_mul_f32_e32 v110, s43, v110
	v_mul_f32_e32 v111, s43, v111
	v_fmac_f32_e32 v10, s59, v108
	v_fmac_f32_e32 v11, s59, v109
	v_fmac_f32_e32 v12, s59, v110
	v_fmac_f32_e32 v13, s59, v111
	v_fmac_f32_e32 v20, s63, v108
	v_fmac_f32_e32 v21, s63, v109
	v_fmac_f32_e32 v14, s63, v110
	v_fmac_f32_e32 v15, s63, v111
	v_fmac_f32_e32 v22, s95, v108
	v_fmac_f32_e32 v23, s95, v109
	v_fmac_f32_e32 v16, s95, v110
	v_fmac_f32_e32 v17, s95, v111
	v_fmac_f32_e32 v24, s99, v108
	v_fmac_f32_e32 v25, s99, v109
	v_fmac_f32_e32 v18, s99, v110
	v_fmac_f32_e32 v19, s99, v111
	s_waitcnt lgkmcnt(0)
	s_load_dwordx4 s[40:43], s[32:33], 0xd0
	s_load_dwordx4 s[56:59], s[0:1], 0xd0
	s_load_dwordx4 s[60:63], s[0:1], 0x2d0
	s_load_dwordx4 s[92:95], s[0:1], 0x4d0
	s_load_dwordx4 s[96:99], s[0:1], 0x6d0
	global_load_dwordx4 v[96:99], v1, s[50:51] offset:-4096
	global_load_dwordx4 v[100:103], v1, s[50:51]
	s_add_u32 s50, s50, 0x2000
	s_addc_u32 s51, s51, 0
	global_load_dwordx4 v[104:107], v1, s[50:51] offset:-4096
	global_load_dwordx4 v[108:111], v1, s[50:51]
	s_add_u32 s50, s50, 0x2000
	s_addc_u32 s51, s51, 0
	s_waitcnt vmcnt(24)
	v_mul_f32_e32 v112, s4, v112
	v_mul_f32_e32 v113, s4, v113
	v_mul_f32_e32 v114, s4, v114
	v_mul_f32_e32 v115, s4, v115
	v_fmac_f32_e32 v10, s12, v112
	v_fmac_f32_e32 v11, s12, v113
	v_fmac_f32_e32 v12, s12, v114
	v_fmac_f32_e32 v13, s12, v115
	v_fmac_f32_e32 v20, s16, v112
	v_fmac_f32_e32 v21, s16, v113
	v_fmac_f32_e32 v14, s16, v114
	v_fmac_f32_e32 v15, s16, v115
	v_fmac_f32_e32 v22, s36, v112
	v_fmac_f32_e32 v23, s36, v113
	v_fmac_f32_e32 v16, s36, v114
	v_fmac_f32_e32 v17, s36, v115
	v_fmac_f32_e32 v24, s64, v112
	v_fmac_f32_e32 v25, s64, v113
	v_fmac_f32_e32 v18, s64, v114
	v_fmac_f32_e32 v19, s64, v115
	v_mul_f32_e32 v116, s5, v116
	v_mul_f32_e32 v117, s5, v117
	v_mul_f32_e32 v118, s5, v118
	v_mul_f32_e32 v119, s5, v119
	v_fmac_f32_e32 v10, s13, v116
	v_fmac_f32_e32 v11, s13, v117
	v_fmac_f32_e32 v12, s13, v118
	v_fmac_f32_e32 v13, s13, v119
	v_fmac_f32_e32 v20, s17, v116
	v_fmac_f32_e32 v21, s17, v117
	v_fmac_f32_e32 v14, s17, v118
	v_fmac_f32_e32 v15, s17, v119
	v_fmac_f32_e32 v22, s37, v116
	v_fmac_f32_e32 v23, s37, v117
	v_fmac_f32_e32 v16, s37, v118
	v_fmac_f32_e32 v17, s37, v119
	v_fmac_f32_e32 v24, s65, v116
	v_fmac_f32_e32 v25, s65, v117
	v_fmac_f32_e32 v18, s65, v118
	v_fmac_f32_e32 v19, s65, v119
	v_mul_f32_e32 v120, s6, v120
	v_mul_f32_e32 v121, s6, v121
	v_mul_f32_e32 v122, s6, v122
	v_mul_f32_e32 v123, s6, v123
	v_fmac_f32_e32 v10, s14, v120
	v_fmac_f32_e32 v11, s14, v121
	v_fmac_f32_e32 v12, s14, v122
	v_fmac_f32_e32 v13, s14, v123
	v_fmac_f32_e32 v20, s18, v120
	v_fmac_f32_e32 v21, s18, v121
	v_fmac_f32_e32 v14, s18, v122
	v_fmac_f32_e32 v15, s18, v123
	v_fmac_f32_e32 v22, s38, v120
	v_fmac_f32_e32 v23, s38, v121
	v_fmac_f32_e32 v16, s38, v122
	v_fmac_f32_e32 v17, s38, v123
	v_fmac_f32_e32 v24, s66, v120
	v_fmac_f32_e32 v25, s66, v121
	v_fmac_f32_e32 v18, s66, v122
	v_fmac_f32_e32 v19, s66, v123
	v_mul_f32_e32 v124, s7, v124
	v_mul_f32_e32 v125, s7, v125
	v_mul_f32_e32 v126, s7, v126
	v_mul_f32_e32 v127, s7, v127
	v_fmac_f32_e32 v10, s15, v124
	v_fmac_f32_e32 v11, s15, v125
	v_fmac_f32_e32 v12, s15, v126
	v_fmac_f32_e32 v13, s15, v127
	v_fmac_f32_e32 v20, s19, v124
	v_fmac_f32_e32 v21, s19, v125
	v_fmac_f32_e32 v14, s19, v126
	v_fmac_f32_e32 v15, s19, v127
	v_fmac_f32_e32 v22, s39, v124
	v_fmac_f32_e32 v23, s39, v125
	v_fmac_f32_e32 v16, s39, v126
	v_fmac_f32_e32 v17, s39, v127
	v_fmac_f32_e32 v24, s67, v124
	v_fmac_f32_e32 v25, s67, v125
	v_fmac_f32_e32 v18, s67, v126
	v_fmac_f32_e32 v19, s67, v127
	s_waitcnt lgkmcnt(0)
; __global__ void __launch_bounds__(512, 2) fwd_kernel(Args a) {
;     ...
;             for (int d = 0; d < 128; ++d) {
;                 const f32x4 wv = *(const f32x4*)(wo + (size_t)d * D) * sc[d];
;                 s0 += wv * pw[d]; s1 += wv * pw[128 + d]; s2 += wv * pw[256 + d]; s3 += wv * pw[384 + d];
;             }
	s_load_dwordx4 s[4:7], s[32:33], 0xe0
	s_load_dwordx4 s[12:15], s[0:1], 0xe0
	s_load_dwordx4 s[16:19], s[0:1], 0x2e0
	s_load_dwordx4 s[36:39], s[0:1], 0x4e0
	s_load_dwordx4 s[64:67], s[0:1], 0x6e0
	global_load_dwordx4 v[112:115], v1, s[50:51] offset:-4096
	global_load_dwordx4 v[116:119], v1, s[50:51]
	s_add_u32 s50, s50, 0x2000
	s_addc_u32 s51, s51, 0
	global_load_dwordx4 v[120:123], v1, s[50:51] offset:-4096
	global_load_dwordx4 v[124:127], v1, s[50:51]
	s_add_u32 s50, s50, 0x2000
	s_addc_u32 s51, s51, 0
	s_waitcnt vmcnt(24)
	v_mul_f32_e32 v128, s40, v128
	v_mul_f32_e32 v129, s40, v129
	v_mul_f32_e32 v130, s40, v130
	v_mul_f32_e32 v131, s40, v131
	v_fmac_f32_e32 v10, s56, v128
	v_fmac_f32_e32 v11, s56, v129
	v_fmac_f32_e32 v12, s56, v130
	v_fmac_f32_e32 v13, s56, v131
	v_fmac_f32_e32 v20, s60, v128
	v_fmac_f32_e32 v21, s60, v129
	v_fmac_f32_e32 v14, s60, v130
	v_fmac_f32_e32 v15, s60, v131
	v_fmac_f32_e32 v22, s92, v128
	v_fmac_f32_e32 v23, s92, v129
	v_fmac_f32_e32 v16, s92, v130
	v_fmac_f32_e32 v17, s92, v131
	v_fmac_f32_e32 v24, s96, v128
	v_fmac_f32_e32 v25, s96, v129
	v_fmac_f32_e32 v18, s96, v130
	v_fmac_f32_e32 v19, s96, v131
	v_mul_f32_e32 v132, s41, v132
	v_mul_f32_e32 v133, s41, v133
	v_mul_f32_e32 v134, s41, v134
	v_mul_f32_e32 v135, s41, v135
	v_fmac_f32_e32 v10, s57, v132
	v_fmac_f32_e32 v11, s57, v133
	v_fmac_f32_e32 v12, s57, v134
	v_fmac_f32_e32 v13, s57, v135
	v_fmac_f32_e32 v20, s61, v132
	v_fmac_f32_e32 v21, s61, v133
	v_fmac_f32_e32 v14, s61, v134
	v_fmac_f32_e32 v15, s61, v135
	v_fmac_f32_e32 v22, s93, v132
	v_fmac_f32_e32 v23, s93, v133
	v_fmac_f32_e32 v16, s93, v134
	v_fmac_f32_e32 v17, s93, v135
	v_fmac_f32_e32 v24, s97, v132
	v_fmac_f32_e32 v25, s97, v133
	v_fmac_f32_e32 v18, s97, v134
	v_fmac_f32_e32 v19, s97, v135
	v_mul_f32_e32 v136, s42, v136
	v_mul_f32_e32 v137, s42, v137
	v_mul_f32_e32 v138, s42, v138
	v_mul_f32_e32 v139, s42, v139
	v_fmac_f32_e32 v10, s58, v136
	v_fmac_f32_e32 v11, s58, v137
	v_fmac_f32_e32 v12, s58, v138
	v_fmac_f32_e32 v13, s58, v139
	v_fmac_f32_e32 v20, s62, v136
	v_fmac_f32_e32 v21, s62, v137
	v_fmac_f32_e32 v14, s62, v138
	v_fmac_f32_e32 v15, s62, v139
	v_fmac_f32_e32 v22, s94, v136
	v_fmac_f32_e32 v23, s94, v137
	v_fmac_f32_e32 v16, s94, v138
	v_fmac_f32_e32 v17, s94, v139
	v_fmac_f32_e32 v24, s98, v136
	v_fmac_f32_e32 v25, s98, v137
	v_fmac_f32_e32 v18, s98, v138
	v_fmac_f32_e32 v19, s98, v139
	v_mul_f32_e32 v140, s43, v140
	v_mul_f32_e32 v141, s43, v141
	v_mul_f32_e32 v142, s43, v142
	v_mul_f32_e32 v143, s43, v143
	v_fmac_f32_e32 v10, s59, v140
	v_fmac_f32_e32 v11, s59, v141
	v_fmac_f32_e32 v12, s59, v142
	v_fmac_f32_e32 v13, s59, v143
	v_fmac_f32_e32 v20, s63, v140
	v_fmac_f32_e32 v21, s63, v141
	v_fmac_f32_e32 v14, s63, v142
	v_fmac_f32_e32 v15, s63, v143
	v_fmac_f32_e32 v22, s95, v140
	v_fmac_f32_e32 v23, s95, v141
	v_fmac_f32_e32 v16, s95, v142
	v_fmac_f32_e32 v17, s95, v143
	v_fmac_f32_e32 v24, s99, v140
	v_fmac_f32_e32 v25, s99, v141
	v_fmac_f32_e32 v18, s99, v142
	v_fmac_f32_e32 v19, s99, v143
	s_waitcnt lgkmcnt(0)
	s_load_dwordx4 s[40:43], s[32:33], 0xf0
	s_load_dwordx4 s[56:59], s[0:1], 0xf0
	s_load_dwordx4 s[60:63], s[0:1], 0x2f0
	s_load_dwordx4 s[92:95], s[0:1], 0x4f0
	s_load_dwordx4 s[96:99], s[0:1], 0x6f0
	global_load_dwordx4 v[128:131], v1, s[50:51] offset:-4096
	global_load_dwordx4 v[132:135], v1, s[50:51]
	s_add_u32 s50, s50, 0x2000
	s_addc_u32 s51, s51, 0
	global_load_dwordx4 v[136:139], v1, s[50:51] offset:-4096
	global_load_dwordx4 v[140:143], v1, s[50:51]
	s_add_u32 s50, s50, 0x2000
	s_addc_u32 s51, s51, 0
	s_waitcnt vmcnt(24)
	v_mul_f32_e32 v32, s4, v32
	v_mul_f32_e32 v33, s4, v33
	v_mul_f32_e32 v34, s4, v34
	v_mul_f32_e32 v35, s4, v35
	v_fmac_f32_e32 v10, s12, v32
	v_fmac_f32_e32 v11, s12, v33
	v_fmac_f32_e32 v12, s12, v34
	v_fmac_f32_e32 v13, s12, v35
	v_fmac_f32_e32 v20, s16, v32
	v_fmac_f32_e32 v21, s16, v33
	v_fmac_f32_e32 v14, s16, v34
	v_fmac_f32_e32 v15, s16, v35
	v_fmac_f32_e32 v22, s36, v32
	v_fmac_f32_e32 v23, s36, v33
	v_fmac_f32_e32 v16, s36, v34
	v_fmac_f32_e32 v17, s36, v35
	v_fmac_f32_e32 v24, s64, v32
	v_fmac_f32_e32 v25, s64, v33
	v_fmac_f32_e32 v18, s64, v34
	v_fmac_f32_e32 v19, s64, v35
	v_mul_f32_e32 v36, s5, v36
	v_mul_f32_e32 v37, s5, v37
	v_mul_f32_e32 v38, s5, v38
	v_mul_f32_e32 v39, s5, v39
	v_fmac_f32_e32 v10, s13, v36
	v_fmac_f32_e32 v11, s13, v37
	v_fmac_f32_e32 v12, s13, v38
	v_fmac_f32_e32 v13, s13, v39
	v_fmac_f32_e32 v20, s17, v36
	v_fmac_f32_e32 v21, s17, v37
	v_fmac_f32_e32 v14, s17, v38
	v_fmac_f32_e32 v15, s17, v39
	v_fmac_f32_e32 v22, s37, v36
	v_fmac_f32_e32 v23, s37, v37
	v_fmac_f32_e32 v16, s37, v38
	v_fmac_f32_e32 v17, s37, v39
	v_fmac_f32_e32 v24, s65, v36
	v_fmac_f32_e32 v25, s65, v37
	v_fmac_f32_e32 v18, s65, v38
	v_fmac_f32_e32 v19, s65, v39
	v_mul_f32_e32 v40, s6, v40
	v_mul_f32_e32 v41, s6, v41
	v_mul_f32_e32 v42, s6, v42
	v_mul_f32_e32 v43, s6, v43
	v_fmac_f32_e32 v10, s14, v40
	v_fmac_f32_e32 v11, s14, v41
	v_fmac_f32_e32 v12, s14, v42
	v_fmac_f32_e32 v13, s14, v43
	v_fmac_f32_e32 v20, s18, v40
	v_fmac_f32_e32 v21, s18, v41
	v_fmac_f32_e32 v14, s18, v42
	v_fmac_f32_e32 v15, s18, v43
	v_fmac_f32_e32 v22, s38, v40
	v_fmac_f32_e32 v23, s38, v41
	v_fmac_f32_e32 v16, s38, v42
	v_fmac_f32_e32 v17, s38, v43
	v_fmac_f32_e32 v24, s66, v40
	v_fmac_f32_e32 v25, s66, v41
	v_fmac_f32_e32 v18, s66, v42
	v_fmac_f32_e32 v19, s66, v43
	v_mul_f32_e32 v44, s7, v44
	v_mul_f32_e32 v45, s7, v45
	v_mul_f32_e32 v46, s7, v46
	v_mul_f32_e32 v47, s7, v47
	v_fmac_f32_e32 v10, s15, v44
	v_fmac_f32_e32 v11, s15, v45
	v_fmac_f32_e32 v12, s15, v46
	v_fmac_f32_e32 v13, s15, v47
	v_fmac_f32_e32 v20, s19, v44
	v_fmac_f32_e32 v21, s19, v45
	v_fmac_f32_e32 v14, s19, v46
	v_fmac_f32_e32 v15, s19, v47
	v_fmac_f32_e32 v22, s39, v44
	v_fmac_f32_e32 v23, s39, v45
	v_fmac_f32_e32 v16, s39, v46
	v_fmac_f32_e32 v17, s39, v47
	v_fmac_f32_e32 v24, s67, v44
	v_fmac_f32_e32 v25, s67, v45
	v_fmac_f32_e32 v18, s67, v46
	v_fmac_f32_e32 v19, s67, v47
	s_waitcnt lgkmcnt(0)
; __global__ void __launch_bounds__(512, 2) fwd_kernel(Args a) {
;     ...
;             for (int d = 0; d < 128; ++d) {
;                 const f32x4 wv = *(const f32x4*)(wo + (size_t)d * D) * sc[d];
;                 s0 += wv * pw[d]; s1 += wv * pw[128 + d]; s2 += wv * pw[256 + d]; s3 += wv * pw[384 + d];
;             }
	s_load_dwordx4 s[4:7], s[32:33], 0x100
	s_load_dwordx4 s[12:15], s[0:1], 0x100
	s_load_dwordx4 s[16:19], s[0:1], 0x300
	s_load_dwordx4 s[36:39], s[0:1], 0x500
	s_load_dwordx4 s[64:67], s[0:1], 0x700
	global_load_dwordx4 v[32:35], v1, s[50:51] offset:-4096
	global_load_dwordx4 v[36:39], v1, s[50:51]
	s_add_u32 s50, s50, 0x2000
	s_addc_u32 s51, s51, 0
	global_load_dwordx4 v[40:43], v1, s[50:51] offset:-4096
	global_load_dwordx4 v[44:47], v1, s[50:51]
	s_add_u32 s50, s50, 0x2000
	s_addc_u32 s51, s51, 0
	s_waitcnt vmcnt(24)
	v_mul_f32_e32 v48, s40, v48
	v_mul_f32_e32 v49, s40, v49
	v_mul_f32_e32 v50, s40, v50
	v_mul_f32_e32 v51, s40, v51
	v_fmac_f32_e32 v10, s56, v48
	v_fmac_f32_e32 v11, s56, v49
	v_fmac_f32_e32 v12, s56, v50
	v_fmac_f32_e32 v13, s56, v51
	v_fmac_f32_e32 v20, s60, v48
	v_fmac_f32_e32 v21, s60, v49
	v_fmac_f32_e32 v14, s60, v50
	v_fmac_f32_e32 v15, s60, v51
	v_fmac_f32_e32 v22, s92, v48
	v_fmac_f32_e32 v23, s92, v49
	v_fmac_f32_e32 v16, s92, v50
	v_fmac_f32_e32 v17, s92, v51
	v_fmac_f32_e32 v24, s96, v48
	v_fmac_f32_e32 v25, s96, v49
	v_fmac_f32_e32 v18, s96, v50
	v_fmac_f32_e32 v19, s96, v51
	v_mul_f32_e32 v52, s41, v52
	v_mul_f32_e32 v53, s41, v53
	v_mul_f32_e32 v54, s41, v54
	v_mul_f32_e32 v55, s41, v55
	v_fmac_f32_e32 v10, s57, v52
	v_fmac_f32_e32 v11, s57, v53
	v_fmac_f32_e32 v12, s57, v54
	v_fmac_f32_e32 v13, s57, v55
	v_fmac_f32_e32 v20, s61, v52
	v_fmac_f32_e32 v21, s61, v53
	v_fmac_f32_e32 v14, s61, v54
	v_fmac_f32_e32 v15, s61, v55
	v_fmac_f32_e32 v22, s93, v52
	v_fmac_f32_e32 v23, s93, v53
	v_fmac_f32_e32 v16, s93, v54
	v_fmac_f32_e32 v17, s93, v55
	v_fmac_f32_e32 v24, s97, v52
	v_fmac_f32_e32 v25, s97, v53
	v_fmac_f32_e32 v18, s97, v54
	v_fmac_f32_e32 v19, s97, v55
	v_mul_f32_e32 v56, s42, v56
	v_mul_f32_e32 v57, s42, v57
	v_mul_f32_e32 v58, s42, v58
	v_mul_f32_e32 v59, s42, v59
	v_fmac_f32_e32 v10, s58, v56
	v_fmac_f32_e32 v11, s58, v57
	v_fmac_f32_e32 v12, s58, v58
	v_fmac_f32_e32 v13, s58, v59
	v_fmac_f32_e32 v20, s62, v56
	v_fmac_f32_e32 v21, s62, v57
	v_fmac_f32_e32 v14, s62, v58
	v_fmac_f32_e32 v15, s62, v59
	v_fmac_f32_e32 v22, s94, v56
	v_fmac_f32_e32 v23, s94, v57
	v_fmac_f32_e32 v16, s94, v58
	v_fmac_f32_e32 v17, s94, v59
	v_fmac_f32_e32 v24, s98, v56
	v_fmac_f32_e32 v25, s98, v57
	v_fmac_f32_e32 v18, s98, v58
	v_fmac_f32_e32 v19, s98, v59
	v_mul_f32_e32 v60, s43, v60
	v_mul_f32_e32 v61, s43, v61
	v_mul_f32_e32 v62, s43, v62
	v_mul_f32_e32 v63, s43, v63
	v_fmac_f32_e32 v10, s59, v60
	v_fmac_f32_e32 v11, s59, v61
	v_fmac_f32_e32 v12, s59, v62
	v_fmac_f32_e32 v13, s59, v63
	v_fmac_f32_e32 v20, s63, v60
	v_fmac_f32_e32 v21, s63, v61
	v_fmac_f32_e32 v14, s63, v62
	v_fmac_f32_e32 v15, s63, v63
	v_fmac_f32_e32 v22, s95, v60
	v_fmac_f32_e32 v23, s95, v61
	v_fmac_f32_e32 v16, s95, v62
	v_fmac_f32_e32 v17, s95, v63
	v_fmac_f32_e32 v24, s99, v60
	v_fmac_f32_e32 v25, s99, v61
	v_fmac_f32_e32 v18, s99, v62
	v_fmac_f32_e32 v19, s99, v63
	s_waitcnt lgkmcnt(0)
	s_load_dwordx4 s[40:43], s[32:33], 0x110
	s_load_dwordx4 s[56:59], s[0:1], 0x110
	s_load_dwordx4 s[60:63], s[0:1], 0x310
	s_load_dwordx4 s[92:95], s[0:1], 0x510
	s_load_dwordx4 s[96:99], s[0:1], 0x710
	global_load_dwordx4 v[48:51], v1, s[50:51] offset:-4096
	global_load_dwordx4 v[52:55], v1, s[50:51]
	s_add_u32 s50, s50, 0x2000
	s_addc_u32 s51, s51, 0
	global_load_dwordx4 v[56:59], v1, s[50:51] offset:-4096
	global_load_dwordx4 v[60:63], v1, s[50:51]
	s_add_u32 s50, s50, 0x2000
	s_addc_u32 s51, s51, 0
	s_waitcnt vmcnt(24)
	v_mul_f32_e32 v64, s4, v64
	v_mul_f32_e32 v65, s4, v65
	v_mul_f32_e32 v66, s4, v66
	v_mul_f32_e32 v67, s4, v67
	v_fmac_f32_e32 v10, s12, v64
	v_fmac_f32_e32 v11, s12, v65
	v_fmac_f32_e32 v12, s12, v66
	v_fmac_f32_e32 v13, s12, v67
	v_fmac_f32_e32 v20, s16, v64
	v_fmac_f32_e32 v21, s16, v65
	v_fmac_f32_e32 v14, s16, v66
	v_fmac_f32_e32 v15, s16, v67
	v_fmac_f32_e32 v22, s36, v64
	v_fmac_f32_e32 v23, s36, v65
	v_fmac_f32_e32 v16, s36, v66
	v_fmac_f32_e32 v17, s36, v67
	v_fmac_f32_e32 v24, s64, v64
	v_fmac_f32_e32 v25, s64, v65
	v_fmac_f32_e32 v18, s64, v66
	v_fmac_f32_e32 v19, s64, v67
	v_mul_f32_e32 v68, s5, v68
	v_mul_f32_e32 v69, s5, v69
	v_mul_f32_e32 v70, s5, v70
	v_mul_f32_e32 v71, s5, v71
	v_fmac_f32_e32 v10, s13, v68
	v_fmac_f32_e32 v11, s13, v69
	v_fmac_f32_e32 v12, s13, v70
	v_fmac_f32_e32 v13, s13, v71
	v_fmac_f32_e32 v20, s17, v68
	v_fmac_f32_e32 v21, s17, v69
	v_fmac_f32_e32 v14, s17, v70
	v_fmac_f32_e32 v15, s17, v71
	v_fmac_f32_e32 v22, s37, v68
	v_fmac_f32_e32 v23, s37, v69
	v_fmac_f32_e32 v16, s37, v70
	v_fmac_f32_e32 v17, s37, v71
	v_fmac_f32_e32 v24, s65, v68
	v_fmac_f32_e32 v25, s65, v69
	v_fmac_f32_e32 v18, s65, v70
	v_fmac_f32_e32 v19, s65, v71
	v_mul_f32_e32 v72, s6, v72
	v_mul_f32_e32 v73, s6, v73
	v_mul_f32_e32 v74, s6, v74
	v_mul_f32_e32 v75, s6, v75
	v_fmac_f32_e32 v10, s14, v72
	v_fmac_f32_e32 v11, s14, v73
	v_fmac_f32_e32 v12, s14, v74
	v_fmac_f32_e32 v13, s14, v75
	v_fmac_f32_e32 v20, s18, v72
	v_fmac_f32_e32 v21, s18, v73
	v_fmac_f32_e32 v14, s18, v74
	v_fmac_f32_e32 v15, s18, v75
	v_fmac_f32_e32 v22, s38, v72
	v_fmac_f32_e32 v23, s38, v73
	v_fmac_f32_e32 v16, s38, v74
	v_fmac_f32_e32 v17, s38, v75
	v_fmac_f32_e32 v24, s66, v72
	v_fmac_f32_e32 v25, s66, v73
	v_fmac_f32_e32 v18, s66, v74
	v_fmac_f32_e32 v19, s66, v75
	v_mul_f32_e32 v76, s7, v76
	v_mul_f32_e32 v77, s7, v77
	v_mul_f32_e32 v78, s7, v78
	v_mul_f32_e32 v79, s7, v79
	v_fmac_f32_e32 v10, s15, v76
	v_fmac_f32_e32 v11, s15, v77
	v_fmac_f32_e32 v12, s15, v78
	v_fmac_f32_e32 v13, s15, v79
	v_fmac_f32_e32 v20, s19, v76
	v_fmac_f32_e32 v21, s19, v77
	v_fmac_f32_e32 v14, s19, v78
	v_fmac_f32_e32 v15, s19, v79
	v_fmac_f32_e32 v22, s39, v76
	v_fmac_f32_e32 v23, s39, v77
	v_fmac_f32_e32 v16, s39, v78
	v_fmac_f32_e32 v17, s39, v79
	v_fmac_f32_e32 v24, s67, v76
	v_fmac_f32_e32 v25, s67, v77
	v_fmac_f32_e32 v18, s67, v78
	v_fmac_f32_e32 v19, s67, v79
	s_waitcnt lgkmcnt(0)
; __global__ void __launch_bounds__(512, 2) fwd_kernel(Args a) {
;     ...
;             for (int d = 0; d < 128; ++d) {
;                 const f32x4 wv = *(const f32x4*)(wo + (size_t)d * D) * sc[d];
;                 s0 += wv * pw[d]; s1 += wv * pw[128 + d]; s2 += wv * pw[256 + d]; s3 += wv * pw[384 + d];
;             }
	s_load_dwordx4 s[4:7], s[32:33], 0x120
	s_load_dwordx4 s[12:15], s[0:1], 0x120
	s_load_dwordx4 s[16:19], s[0:1], 0x320
	s_load_dwordx4 s[36:39], s[0:1], 0x520
	s_load_dwordx4 s[64:67], s[0:1], 0x720
	global_load_dwordx4 v[64:67], v1, s[50:51] offset:-4096
	global_load_dwordx4 v[68:71], v1, s[50:51]
	s_add_u32 s50, s50, 0x2000
	s_addc_u32 s51, s51, 0
	global_load_dwordx4 v[72:75], v1, s[50:51] offset:-4096
	global_load_dwordx4 v[76:79], v1, s[50:51]
	s_add_u32 s50, s50, 0x2000
	s_addc_u32 s51, s51, 0
	s_waitcnt vmcnt(24)
	v_mul_f32_e32 v80, s40, v80
	v_mul_f32_e32 v81, s40, v81
	v_mul_f32_e32 v82, s40, v82
	v_mul_f32_e32 v83, s40, v83
	v_fmac_f32_e32 v10, s56, v80
	v_fmac_f32_e32 v11, s56, v81
	v_fmac_f32_e32 v12, s56, v82
	v_fmac_f32_e32 v13, s56, v83
	v_fmac_f32_e32 v20, s60, v80
	v_fmac_f32_e32 v21, s60, v81
	v_fmac_f32_e32 v14, s60, v82
	v_fmac_f32_e32 v15, s60, v83
	v_fmac_f32_e32 v22, s92, v80
	v_fmac_f32_e32 v23, s92, v81
	v_fmac_f32_e32 v16, s92, v82
	v_fmac_f32_e32 v17, s92, v83
	v_fmac_f32_e32 v24, s96, v80
	v_fmac_f32_e32 v25, s96, v81
	v_fmac_f32_e32 v18, s96, v82
	v_fmac_f32_e32 v19, s96, v83
	v_mul_f32_e32 v84, s41, v84
	v_mul_f32_e32 v85, s41, v85
	v_mul_f32_e32 v86, s41, v86
	v_mul_f32_e32 v87, s41, v87
	v_fmac_f32_e32 v10, s57, v84
	v_fmac_f32_e32 v11, s57, v85
	v_fmac_f32_e32 v12, s57, v86
	v_fmac_f32_e32 v13, s57, v87
	v_fmac_f32_e32 v20, s61, v84
	v_fmac_f32_e32 v21, s61, v85
	v_fmac_f32_e32 v14, s61, v86
	v_fmac_f32_e32 v15, s61, v87
	v_fmac_f32_e32 v22, s93, v84
	v_fmac_f32_e32 v23, s93, v85
	v_fmac_f32_e32 v16, s93, v86
	v_fmac_f32_e32 v17, s93, v87
	v_fmac_f32_e32 v24, s97, v84
	v_fmac_f32_e32 v25, s97, v85
	v_fmac_f32_e32 v18, s97, v86
	v_fmac_f32_e32 v19, s97, v87
	v_mul_f32_e32 v88, s42, v88
	v_mul_f32_e32 v89, s42, v89
	v_mul_f32_e32 v90, s42, v90
	v_mul_f32_e32 v91, s42, v91
	v_fmac_f32_e32 v10, s58, v88
	v_fmac_f32_e32 v11, s58, v89
	v_fmac_f32_e32 v12, s58, v90
	v_fmac_f32_e32 v13, s58, v91
	v_fmac_f32_e32 v20, s62, v88
	v_fmac_f32_e32 v21, s62, v89
	v_fmac_f32_e32 v14, s62, v90
	v_fmac_f32_e32 v15, s62, v91
	v_fmac_f32_e32 v22, s94, v88
	v_fmac_f32_e32 v23, s94, v89
	v_fmac_f32_e32 v16, s94, v90
	v_fmac_f32_e32 v17, s94, v91
	v_fmac_f32_e32 v24, s98, v88
	v_fmac_f32_e32 v25, s98, v89
	v_fmac_f32_e32 v18, s98, v90
	v_fmac_f32_e32 v19, s98, v91
	v_mul_f32_e32 v92, s43, v92
	v_mul_f32_e32 v93, s43, v93
	v_mul_f32_e32 v94, s43, v94
	v_mul_f32_e32 v95, s43, v95
	v_fmac_f32_e32 v10, s59, v92
	v_fmac_f32_e32 v11, s59, v93
	v_fmac_f32_e32 v12, s59, v94
	v_fmac_f32_e32 v13, s59, v95
	v_fmac_f32_e32 v20, s63, v92
	v_fmac_f32_e32 v21, s63, v93
	v_fmac_f32_e32 v14, s63, v94
	v_fmac_f32_e32 v15, s63, v95
	v_fmac_f32_e32 v22, s95, v92
	v_fmac_f32_e32 v23, s95, v93
	v_fmac_f32_e32 v16, s95, v94
	v_fmac_f32_e32 v17, s95, v95
	v_fmac_f32_e32 v24, s99, v92
	v_fmac_f32_e32 v25, s99, v93
	v_fmac_f32_e32 v18, s99, v94
	v_fmac_f32_e32 v19, s99, v95
	s_waitcnt lgkmcnt(0)
	s_load_dwordx4 s[40:43], s[32:33], 0x130
	s_load_dwordx4 s[56:59], s[0:1], 0x130
	s_load_dwordx4 s[60:63], s[0:1], 0x330
	s_load_dwordx4 s[92:95], s[0:1], 0x530
	s_load_dwordx4 s[96:99], s[0:1], 0x730
	global_load_dwordx4 v[80:83], v1, s[50:51] offset:-4096
	global_load_dwordx4 v[84:87], v1, s[50:51]
	s_add_u32 s50, s50, 0x2000
	s_addc_u32 s51, s51, 0
	global_load_dwordx4 v[88:91], v1, s[50:51] offset:-4096
	global_load_dwordx4 v[92:95], v1, s[50:51]
	s_add_u32 s50, s50, 0x2000
	s_addc_u32 s51, s51, 0
	s_waitcnt vmcnt(24)
	v_mul_f32_e32 v96, s4, v96
	v_mul_f32_e32 v97, s4, v97
	v_mul_f32_e32 v98, s4, v98
	v_mul_f32_e32 v99, s4, v99
	v_fmac_f32_e32 v10, s12, v96
	v_fmac_f32_e32 v11, s12, v97
	v_fmac_f32_e32 v12, s12, v98
	v_fmac_f32_e32 v13, s12, v99
	v_fmac_f32_e32 v20, s16, v96
	v_fmac_f32_e32 v21, s16, v97
	v_fmac_f32_e32 v14, s16, v98
	v_fmac_f32_e32 v15, s16, v99
	v_fmac_f32_e32 v22, s36, v96
	v_fmac_f32_e32 v23, s36, v97
	v_fmac_f32_e32 v16, s36, v98
	v_fmac_f32_e32 v17, s36, v99
	v_fmac_f32_e32 v24, s64, v96
	v_fmac_f32_e32 v25, s64, v97
	v_fmac_f32_e32 v18, s64, v98
	v_fmac_f32_e32 v19, s64, v99
	v_mul_f32_e32 v100, s5, v100
	v_mul_f32_e32 v101, s5, v101
	v_mul_f32_e32 v102, s5, v102
	v_mul_f32_e32 v103, s5, v103
	v_fmac_f32_e32 v10, s13, v100
	v_fmac_f32_e32 v11, s13, v101
	v_fmac_f32_e32 v12, s13, v102
	v_fmac_f32_e32 v13, s13, v103
	v_fmac_f32_e32 v20, s17, v100
	v_fmac_f32_e32 v21, s17, v101
	v_fmac_f32_e32 v14, s17, v102
	v_fmac_f32_e32 v15, s17, v103
	v_fmac_f32_e32 v22, s37, v100
	v_fmac_f32_e32 v23, s37, v101
	v_fmac_f32_e32 v16, s37, v102
	v_fmac_f32_e32 v17, s37, v103
	v_fmac_f32_e32 v24, s65, v100
	v_fmac_f32_e32 v25, s65, v101
	v_fmac_f32_e32 v18, s65, v102
	v_fmac_f32_e32 v19, s65, v103
	v_mul_f32_e32 v104, s6, v104
	v_mul_f32_e32 v105, s6, v105
	v_mul_f32_e32 v106, s6, v106
	v_mul_f32_e32 v107, s6, v107
	v_fmac_f32_e32 v10, s14, v104
	v_fmac_f32_e32 v11, s14, v105
	v_fmac_f32_e32 v12, s14, v106
	v_fmac_f32_e32 v13, s14, v107
	v_fmac_f32_e32 v20, s18, v104
	v_fmac_f32_e32 v21, s18, v105
	v_fmac_f32_e32 v14, s18, v106
	v_fmac_f32_e32 v15, s18, v107
	v_fmac_f32_e32 v22, s38, v104
	v_fmac_f32_e32 v23, s38, v105
	v_fmac_f32_e32 v16, s38, v106
	v_fmac_f32_e32 v17, s38, v107
	v_fmac_f32_e32 v24, s66, v104
	v_fmac_f32_e32 v25, s66, v105
	v_fmac_f32_e32 v18, s66, v106
	v_fmac_f32_e32 v19, s66, v107
	v_mul_f32_e32 v108, s7, v108
	v_mul_f32_e32 v109, s7, v109
	v_mul_f32_e32 v110, s7, v110
	v_mul_f32_e32 v111, s7, v111
	v_fmac_f32_e32 v10, s15, v108
	v_fmac_f32_e32 v11, s15, v109
	v_fmac_f32_e32 v12, s15, v110
	v_fmac_f32_e32 v13, s15, v111
	v_fmac_f32_e32 v20, s19, v108
	v_fmac_f32_e32 v21, s19, v109
	v_fmac_f32_e32 v14, s19, v110
	v_fmac_f32_e32 v15, s19, v111
	v_fmac_f32_e32 v22, s39, v108
	v_fmac_f32_e32 v23, s39, v109
	v_fmac_f32_e32 v16, s39, v110
	v_fmac_f32_e32 v17, s39, v111
	v_fmac_f32_e32 v24, s67, v108
	v_fmac_f32_e32 v25, s67, v109
	v_fmac_f32_e32 v18, s67, v110
	v_fmac_f32_e32 v19, s67, v111
	s_waitcnt lgkmcnt(0)
; __global__ void __launch_bounds__(512, 2) fwd_kernel(Args a) {
;     ...
;             for (int d = 0; d < 128; ++d) {
;                 const f32x4 wv = *(const f32x4*)(wo + (size_t)d * D) * sc[d];
;                 s0 += wv * pw[d]; s1 += wv * pw[128 + d]; s2 += wv * pw[256 + d]; s3 += wv * pw[384 + d];
;             }
	s_load_dwordx4 s[4:7], s[32:33], 0x140
	s_load_dwordx4 s[12:15], s[0:1], 0x140
	s_load_dwordx4 s[16:19], s[0:1], 0x340
	s_load_dwordx4 s[36:39], s[0:1], 0x540
	s_load_dwordx4 s[64:67], s[0:1], 0x740
	global_load_dwordx4 v[96:99], v1, s[50:51] offset:-4096
	global_load_dwordx4 v[100:103], v1, s[50:51]
	s_add_u32 s50, s50, 0x2000
	s_addc_u32 s51, s51, 0
	global_load_dwordx4 v[104:107], v1, s[50:51] offset:-4096
	global_load_dwordx4 v[108:111], v1, s[50:51]
	s_add_u32 s50, s50, 0x2000
	s_addc_u32 s51, s51, 0
	s_waitcnt vmcnt(24)
	v_mul_f32_e32 v112, s40, v112
	v_mul_f32_e32 v113, s40, v113
	v_mul_f32_e32 v114, s40, v114
	v_mul_f32_e32 v115, s40, v115
	v_fmac_f32_e32 v10, s56, v112
	v_fmac_f32_e32 v11, s56, v113
	v_fmac_f32_e32 v12, s56, v114
	v_fmac_f32_e32 v13, s56, v115
	v_fmac_f32_e32 v20, s60, v112
	v_fmac_f32_e32 v21, s60, v113
	v_fmac_f32_e32 v14, s60, v114
	v_fmac_f32_e32 v15, s60, v115
	v_fmac_f32_e32 v22, s92, v112
	v_fmac_f32_e32 v23, s92, v113
	v_fmac_f32_e32 v16, s92, v114
	v_fmac_f32_e32 v17, s92, v115
	v_fmac_f32_e32 v24, s96, v112
	v_fmac_f32_e32 v25, s96, v113
	v_fmac_f32_e32 v18, s96, v114
	v_fmac_f32_e32 v19, s96, v115
	v_mul_f32_e32 v116, s41, v116
	v_mul_f32_e32 v117, s41, v117
	v_mul_f32_e32 v118, s41, v118
	v_mul_f32_e32 v119, s41, v119
	v_fmac_f32_e32 v10, s57, v116
	v_fmac_f32_e32 v11, s57, v117
	v_fmac_f32_e32 v12, s57, v118
	v_fmac_f32_e32 v13, s57, v119
	v_fmac_f32_e32 v20, s61, v116
	v_fmac_f32_e32 v21, s61, v117
	v_fmac_f32_e32 v14, s61, v118
	v_fmac_f32_e32 v15, s61, v119
	v_fmac_f32_e32 v22, s93, v116
	v_fmac_f32_e32 v23, s93, v117
	v_fmac_f32_e32 v16, s93, v118
	v_fmac_f32_e32 v17, s93, v119
	v_fmac_f32_e32 v24, s97, v116
	v_fmac_f32_e32 v25, s97, v117
	v_fmac_f32_e32 v18, s97, v118
	v_fmac_f32_e32 v19, s97, v119
	v_mul_f32_e32 v120, s42, v120
	v_mul_f32_e32 v121, s42, v121
	v_mul_f32_e32 v122, s42, v122
	v_mul_f32_e32 v123, s42, v123
	v_fmac_f32_e32 v10, s58, v120
	v_fmac_f32_e32 v11, s58, v121
	v_fmac_f32_e32 v12, s58, v122
	v_fmac_f32_e32 v13, s58, v123
	v_fmac_f32_e32 v20, s62, v120
	v_fmac_f32_e32 v21, s62, v121
	v_fmac_f32_e32 v14, s62, v122
	v_fmac_f32_e32 v15, s62, v123
	v_fmac_f32_e32 v22, s94, v120
	v_fmac_f32_e32 v23, s94, v121
	v_fmac_f32_e32 v16, s94, v122
	v_fmac_f32_e32 v17, s94, v123
	v_fmac_f32_e32 v24, s98, v120
	v_fmac_f32_e32 v25, s98, v121
	v_fmac_f32_e32 v18, s98, v122
	v_fmac_f32_e32 v19, s98, v123
	v_mul_f32_e32 v124, s43, v124
	v_mul_f32_e32 v125, s43, v125
	v_mul_f32_e32 v126, s43, v126
	v_mul_f32_e32 v127, s43, v127
	v_fmac_f32_e32 v10, s59, v124
	v_fmac_f32_e32 v11, s59, v125
	v_fmac_f32_e32 v12, s59, v126
	v_fmac_f32_e32 v13, s59, v127
	v_fmac_f32_e32 v20, s63, v124
	v_fmac_f32_e32 v21, s63, v125
	v_fmac_f32_e32 v14, s63, v126
	v_fmac_f32_e32 v15, s63, v127
	v_fmac_f32_e32 v22, s95, v124
	v_fmac_f32_e32 v23, s95, v125
	v_fmac_f32_e32 v16, s95, v126
	v_fmac_f32_e32 v17, s95, v127
	v_fmac_f32_e32 v24, s99, v124
	v_fmac_f32_e32 v25, s99, v125
	v_fmac_f32_e32 v18, s99, v126
	v_fmac_f32_e32 v19, s99, v127
	s_waitcnt lgkmcnt(0)
	s_load_dwordx4 s[40:43], s[32:33], 0x150
	s_load_dwordx4 s[56:59], s[0:1], 0x150
	s_load_dwordx4 s[60:63], s[0:1], 0x350
	s_load_dwordx4 s[92:95], s[0:1], 0x550
	s_load_dwordx4 s[96:99], s[0:1], 0x750
	global_load_dwordx4 v[112:115], v1, s[50:51] offset:-4096
	global_load_dwordx4 v[116:119], v1, s[50:51]
	s_add_u32 s50, s50, 0x2000
	s_addc_u32 s51, s51, 0
	global_load_dwordx4 v[120:123], v1, s[50:51] offset:-4096
	global_load_dwordx4 v[124:127], v1, s[50:51]
	s_add_u32 s50, s50, 0x2000
	s_addc_u32 s51, s51, 0
	s_waitcnt vmcnt(24)
	v_mul_f32_e32 v128, s4, v128
	v_mul_f32_e32 v129, s4, v129
	v_mul_f32_e32 v130, s4, v130
	v_mul_f32_e32 v131, s4, v131
	v_fmac_f32_e32 v10, s12, v128
	v_fmac_f32_e32 v11, s12, v129
	v_fmac_f32_e32 v12, s12, v130
	v_fmac_f32_e32 v13, s12, v131
	v_fmac_f32_e32 v20, s16, v128
	v_fmac_f32_e32 v21, s16, v129
	v_fmac_f32_e32 v14, s16, v130
	v_fmac_f32_e32 v15, s16, v131
	v_fmac_f32_e32 v22, s36, v128
	v_fmac_f32_e32 v23, s36, v129
	v_fmac_f32_e32 v16, s36, v130
	v_fmac_f32_e32 v17, s36, v131
	v_fmac_f32_e32 v24, s64, v128
	v_fmac_f32_e32 v25, s64, v129
	v_fmac_f32_e32 v18, s64, v130
	v_fmac_f32_e32 v19, s64, v131
	v_mul_f32_e32 v132, s5, v132
	v_mul_f32_e32 v133, s5, v133
	v_mul_f32_e32 v134, s5, v134
	v_mul_f32_e32 v135, s5, v135
	v_fmac_f32_e32 v10, s13, v132
	v_fmac_f32_e32 v11, s13, v133
	v_fmac_f32_e32 v12, s13, v134
	v_fmac_f32_e32 v13, s13, v135
	v_fmac_f32_e32 v20, s17, v132
	v_fmac_f32_e32 v21, s17, v133
	v_fmac_f32_e32 v14, s17, v134
	v_fmac_f32_e32 v15, s17, v135
	v_fmac_f32_e32 v22, s37, v132
	v_fmac_f32_e32 v23, s37, v133
	v_fmac_f32_e32 v16, s37, v134
	v_fmac_f32_e32 v17, s37, v135
	v_fmac_f32_e32 v24, s65, v132
	v_fmac_f32_e32 v25, s65, v133
	v_fmac_f32_e32 v18, s65, v134
	v_fmac_f32_e32 v19, s65, v135
	v_mul_f32_e32 v136, s6, v136
	v_mul_f32_e32 v137, s6, v137
	v_mul_f32_e32 v138, s6, v138
	v_mul_f32_e32 v139, s6, v139
	v_fmac_f32_e32 v10, s14, v136
	v_fmac_f32_e32 v11, s14, v137
	v_fmac_f32_e32 v12, s14, v138
	v_fmac_f32_e32 v13, s14, v139
	v_fmac_f32_e32 v20, s18, v136
	v_fmac_f32_e32 v21, s18, v137
	v_fmac_f32_e32 v14, s18, v138
	v_fmac_f32_e32 v15, s18, v139
	v_fmac_f32_e32 v22, s38, v136
	v_fmac_f32_e32 v23, s38, v137
	v_fmac_f32_e32 v16, s38, v138
	v_fmac_f32_e32 v17, s38, v139
	v_fmac_f32_e32 v24, s66, v136
	v_fmac_f32_e32 v25, s66, v137
	v_fmac_f32_e32 v18, s66, v138
	v_fmac_f32_e32 v19, s66, v139
	v_mul_f32_e32 v140, s7, v140
	v_mul_f32_e32 v141, s7, v141
	v_mul_f32_e32 v142, s7, v142
	v_mul_f32_e32 v143, s7, v143
	v_fmac_f32_e32 v10, s15, v140
	v_fmac_f32_e32 v11, s15, v141
	v_fmac_f32_e32 v12, s15, v142
	v_fmac_f32_e32 v13, s15, v143
	v_fmac_f32_e32 v20, s19, v140
	v_fmac_f32_e32 v21, s19, v141
	v_fmac_f32_e32 v14, s19, v142
	v_fmac_f32_e32 v15, s19, v143
	v_fmac_f32_e32 v22, s39, v140
	v_fmac_f32_e32 v23, s39, v141
	v_fmac_f32_e32 v16, s39, v142
	v_fmac_f32_e32 v17, s39, v143
	v_fmac_f32_e32 v24, s67, v140
	v_fmac_f32_e32 v25, s67, v141
	v_fmac_f32_e32 v18, s67, v142
	v_fmac_f32_e32 v19, s67, v143
	s_waitcnt lgkmcnt(0)
; __global__ void __launch_bounds__(512, 2) fwd_kernel(Args a) {
;     ...
;             for (int d = 0; d < 128; ++d) {
;                 const f32x4 wv = *(const f32x4*)(wo + (size_t)d * D) * sc[d];
;                 s0 += wv * pw[d]; s1 += wv * pw[128 + d]; s2 += wv * pw[256 + d]; s3 += wv * pw[384 + d];
;             }
	s_load_dwordx4 s[4:7], s[32:33], 0x160
	s_load_dwordx4 s[12:15], s[0:1], 0x160
	s_load_dwordx4 s[16:19], s[0:1], 0x360
	s_load_dwordx4 s[36:39], s[0:1], 0x560
	s_load_dwordx4 s[64:67], s[0:1], 0x760
	global_load_dwordx4 v[128:131], v1, s[50:51] offset:-4096
	global_load_dwordx4 v[132:135], v1, s[50:51]
	s_add_u32 s50, s50, 0x2000
	s_addc_u32 s51, s51, 0
	global_load_dwordx4 v[136:139], v1, s[50:51] offset:-4096
	global_load_dwordx4 v[140:143], v1, s[50:51]
	s_add_u32 s50, s50, 0x2000
	s_addc_u32 s51, s51, 0
	s_waitcnt vmcnt(24)
	v_mul_f32_e32 v32, s40, v32
	v_mul_f32_e32 v33, s40, v33
	v_mul_f32_e32 v34, s40, v34
	v_mul_f32_e32 v35, s40, v35
	v_fmac_f32_e32 v10, s56, v32
	v_fmac_f32_e32 v11, s56, v33
	v_fmac_f32_e32 v12, s56, v34
	v_fmac_f32_e32 v13, s56, v35
	v_fmac_f32_e32 v20, s60, v32
	v_fmac_f32_e32 v21, s60, v33
	v_fmac_f32_e32 v14, s60, v34
	v_fmac_f32_e32 v15, s60, v35
	v_fmac_f32_e32 v22, s92, v32
	v_fmac_f32_e32 v23, s92, v33
	v_fmac_f32_e32 v16, s92, v34
	v_fmac_f32_e32 v17, s92, v35
	v_fmac_f32_e32 v24, s96, v32
	v_fmac_f32_e32 v25, s96, v33
	v_fmac_f32_e32 v18, s96, v34
	v_fmac_f32_e32 v19, s96, v35
	v_mul_f32_e32 v36, s41, v36
	v_mul_f32_e32 v37, s41, v37
	v_mul_f32_e32 v38, s41, v38
	v_mul_f32_e32 v39, s41, v39
	v_fmac_f32_e32 v10, s57, v36
	v_fmac_f32_e32 v11, s57, v37
	v_fmac_f32_e32 v12, s57, v38
	v_fmac_f32_e32 v13, s57, v39
	v_fmac_f32_e32 v20, s61, v36
	v_fmac_f32_e32 v21, s61, v37
	v_fmac_f32_e32 v14, s61, v38
	v_fmac_f32_e32 v15, s61, v39
	v_fmac_f32_e32 v22, s93, v36
	v_fmac_f32_e32 v23, s93, v37
	v_fmac_f32_e32 v16, s93, v38
	v_fmac_f32_e32 v17, s93, v39
	v_fmac_f32_e32 v24, s97, v36
	v_fmac_f32_e32 v25, s97, v37
	v_fmac_f32_e32 v18, s97, v38
	v_fmac_f32_e32 v19, s97, v39
	v_mul_f32_e32 v40, s42, v40
	v_mul_f32_e32 v41, s42, v41
	v_mul_f32_e32 v42, s42, v42
	v_mul_f32_e32 v43, s42, v43
	v_fmac_f32_e32 v10, s58, v40
	v_fmac_f32_e32 v11, s58, v41
	v_fmac_f32_e32 v12, s58, v42
	v_fmac_f32_e32 v13, s58, v43
	v_fmac_f32_e32 v20, s62, v40
	v_fmac_f32_e32 v21, s62, v41
	v_fmac_f32_e32 v14, s62, v42
	v_fmac_f32_e32 v15, s62, v43
	v_fmac_f32_e32 v22, s94, v40
	v_fmac_f32_e32 v23, s94, v41
	v_fmac_f32_e32 v16, s94, v42
	v_fmac_f32_e32 v17, s94, v43
	v_fmac_f32_e32 v24, s98, v40
	v_fmac_f32_e32 v25, s98, v41
	v_fmac_f32_e32 v18, s98, v42
	v_fmac_f32_e32 v19, s98, v43
	v_mul_f32_e32 v44, s43, v44
	v_mul_f32_e32 v45, s43, v45
	v_mul_f32_e32 v46, s43, v46
	v_mul_f32_e32 v47, s43, v47
	v_fmac_f32_e32 v10, s59, v44
	v_fmac_f32_e32 v11, s59, v45
	v_fmac_f32_e32 v12, s59, v46
	v_fmac_f32_e32 v13, s59, v47
	v_fmac_f32_e32 v20, s63, v44
	v_fmac_f32_e32 v21, s63, v45
	v_fmac_f32_e32 v14, s63, v46
	v_fmac_f32_e32 v15, s63, v47
	v_fmac_f32_e32 v22, s95, v44
	v_fmac_f32_e32 v23, s95, v45
	v_fmac_f32_e32 v16, s95, v46
	v_fmac_f32_e32 v17, s95, v47
	v_fmac_f32_e32 v24, s99, v44
	v_fmac_f32_e32 v25, s99, v45
	v_fmac_f32_e32 v18, s99, v46
	v_fmac_f32_e32 v19, s99, v47
	s_waitcnt lgkmcnt(0)
	s_load_dwordx4 s[40:43], s[32:33], 0x170
	s_load_dwordx4 s[56:59], s[0:1], 0x170
	s_load_dwordx4 s[60:63], s[0:1], 0x370
	s_load_dwordx4 s[92:95], s[0:1], 0x570
	s_load_dwordx4 s[96:99], s[0:1], 0x770
	global_load_dwordx4 v[32:35], v1, s[50:51] offset:-4096
	global_load_dwordx4 v[36:39], v1, s[50:51]
	s_add_u32 s50, s50, 0x2000
	s_addc_u32 s51, s51, 0
	global_load_dwordx4 v[40:43], v1, s[50:51] offset:-4096
	global_load_dwordx4 v[44:47], v1, s[50:51]
	s_add_u32 s50, s50, 0x2000
	s_addc_u32 s51, s51, 0
	s_waitcnt vmcnt(24)
	v_mul_f32_e32 v48, s4, v48
	v_mul_f32_e32 v49, s4, v49
	v_mul_f32_e32 v50, s4, v50
	v_mul_f32_e32 v51, s4, v51
	v_fmac_f32_e32 v10, s12, v48
	v_fmac_f32_e32 v11, s12, v49
	v_fmac_f32_e32 v12, s12, v50
	v_fmac_f32_e32 v13, s12, v51
	v_fmac_f32_e32 v20, s16, v48
	v_fmac_f32_e32 v21, s16, v49
	v_fmac_f32_e32 v14, s16, v50
	v_fmac_f32_e32 v15, s16, v51
	v_fmac_f32_e32 v22, s36, v48
	v_fmac_f32_e32 v23, s36, v49
	v_fmac_f32_e32 v16, s36, v50
	v_fmac_f32_e32 v17, s36, v51
	v_fmac_f32_e32 v24, s64, v48
	v_fmac_f32_e32 v25, s64, v49
	v_fmac_f32_e32 v18, s64, v50
	v_fmac_f32_e32 v19, s64, v51
	v_mul_f32_e32 v52, s5, v52
	v_mul_f32_e32 v53, s5, v53
	v_mul_f32_e32 v54, s5, v54
	v_mul_f32_e32 v55, s5, v55
	v_fmac_f32_e32 v10, s13, v52
	v_fmac_f32_e32 v11, s13, v53
	v_fmac_f32_e32 v12, s13, v54
	v_fmac_f32_e32 v13, s13, v55
	v_fmac_f32_e32 v20, s17, v52
	v_fmac_f32_e32 v21, s17, v53
	v_fmac_f32_e32 v14, s17, v54
	v_fmac_f32_e32 v15, s17, v55
	v_fmac_f32_e32 v22, s37, v52
	v_fmac_f32_e32 v23, s37, v53
	v_fmac_f32_e32 v16, s37, v54
	v_fmac_f32_e32 v17, s37, v55
	v_fmac_f32_e32 v24, s65, v52
	v_fmac_f32_e32 v25, s65, v53
	v_fmac_f32_e32 v18, s65, v54
	v_fmac_f32_e32 v19, s65, v55
	v_mul_f32_e32 v56, s6, v56
	v_mul_f32_e32 v57, s6, v57
	v_mul_f32_e32 v58, s6, v58
	v_mul_f32_e32 v59, s6, v59
	v_fmac_f32_e32 v10, s14, v56
	v_fmac_f32_e32 v11, s14, v57
	v_fmac_f32_e32 v12, s14, v58
	v_fmac_f32_e32 v13, s14, v59
	v_fmac_f32_e32 v20, s18, v56
	v_fmac_f32_e32 v21, s18, v57
	v_fmac_f32_e32 v14, s18, v58
	v_fmac_f32_e32 v15, s18, v59
	v_fmac_f32_e32 v22, s38, v56
	v_fmac_f32_e32 v23, s38, v57
	v_fmac_f32_e32 v16, s38, v58
	v_fmac_f32_e32 v17, s38, v59
	v_fmac_f32_e32 v24, s66, v56
	v_fmac_f32_e32 v25, s66, v57
	v_fmac_f32_e32 v18, s66, v58
	v_fmac_f32_e32 v19, s66, v59
	v_mul_f32_e32 v60, s7, v60
	v_mul_f32_e32 v61, s7, v61
	v_mul_f32_e32 v62, s7, v62
	v_mul_f32_e32 v63, s7, v63
	v_fmac_f32_e32 v10, s15, v60
	v_fmac_f32_e32 v11, s15, v61
	v_fmac_f32_e32 v12, s15, v62
	v_fmac_f32_e32 v13, s15, v63
	v_fmac_f32_e32 v20, s19, v60
	v_fmac_f32_e32 v21, s19, v61
	v_fmac_f32_e32 v14, s19, v62
	v_fmac_f32_e32 v15, s19, v63
	v_fmac_f32_e32 v22, s39, v60
	v_fmac_f32_e32 v23, s39, v61
	v_fmac_f32_e32 v16, s39, v62
	v_fmac_f32_e32 v17, s39, v63
	v_fmac_f32_e32 v24, s67, v60
	v_fmac_f32_e32 v25, s67, v61
	v_fmac_f32_e32 v18, s67, v62
	v_fmac_f32_e32 v19, s67, v63
	s_waitcnt lgkmcnt(0)
; __global__ void __launch_bounds__(512, 2) fwd_kernel(Args a) {
;     ...
;             for (int d = 0; d < 128; ++d) {
;                 const f32x4 wv = *(const f32x4*)(wo + (size_t)d * D) * sc[d];
;                 s0 += wv * pw[d]; s1 += wv * pw[128 + d]; s2 += wv * pw[256 + d]; s3 += wv * pw[384 + d];
;             }
	s_load_dwordx4 s[4:7], s[32:33], 0x180
	s_load_dwordx4 s[12:15], s[0:1], 0x180
	s_load_dwordx4 s[16:19], s[0:1], 0x380
	s_load_dwordx4 s[36:39], s[0:1], 0x580
	s_load_dwordx4 s[64:67], s[0:1], 0x780
	global_load_dwordx4 v[48:51], v1, s[50:51] offset:-4096
	global_load_dwordx4 v[52:55], v1, s[50:51]
	s_add_u32 s50, s50, 0x2000
	s_addc_u32 s51, s51, 0
	global_load_dwordx4 v[56:59], v1, s[50:51] offset:-4096
	global_load_dwordx4 v[60:63], v1, s[50:51]
	s_add_u32 s50, s50, 0x2000
	s_addc_u32 s51, s51, 0
	s_waitcnt vmcnt(24)
	v_mul_f32_e32 v64, s40, v64
	v_mul_f32_e32 v65, s40, v65
	v_mul_f32_e32 v66, s40, v66
	v_mul_f32_e32 v67, s40, v67
	v_fmac_f32_e32 v10, s56, v64
	v_fmac_f32_e32 v11, s56, v65
	v_fmac_f32_e32 v12, s56, v66
	v_fmac_f32_e32 v13, s56, v67
	v_fmac_f32_e32 v20, s60, v64
	v_fmac_f32_e32 v21, s60, v65
	v_fmac_f32_e32 v14, s60, v66
	v_fmac_f32_e32 v15, s60, v67
	v_fmac_f32_e32 v22, s92, v64
	v_fmac_f32_e32 v23, s92, v65
	v_fmac_f32_e32 v16, s92, v66
	v_fmac_f32_e32 v17, s92, v67
	v_fmac_f32_e32 v24, s96, v64
	v_fmac_f32_e32 v25, s96, v65
	v_fmac_f32_e32 v18, s96, v66
	v_fmac_f32_e32 v19, s96, v67
	v_mul_f32_e32 v68, s41, v68
	v_mul_f32_e32 v69, s41, v69
	v_mul_f32_e32 v70, s41, v70
	v_mul_f32_e32 v71, s41, v71
	v_fmac_f32_e32 v10, s57, v68
	v_fmac_f32_e32 v11, s57, v69
	v_fmac_f32_e32 v12, s57, v70
	v_fmac_f32_e32 v13, s57, v71
	v_fmac_f32_e32 v20, s61, v68
	v_fmac_f32_e32 v21, s61, v69
	v_fmac_f32_e32 v14, s61, v70
	v_fmac_f32_e32 v15, s61, v71
	v_fmac_f32_e32 v22, s93, v68
	v_fmac_f32_e32 v23, s93, v69
	v_fmac_f32_e32 v16, s93, v70
	v_fmac_f32_e32 v17, s93, v71
	v_fmac_f32_e32 v24, s97, v68
	v_fmac_f32_e32 v25, s97, v69
	v_fmac_f32_e32 v18, s97, v70
	v_fmac_f32_e32 v19, s97, v71
	v_mul_f32_e32 v72, s42, v72
	v_mul_f32_e32 v73, s42, v73
	v_mul_f32_e32 v74, s42, v74
	v_mul_f32_e32 v75, s42, v75
	v_fmac_f32_e32 v10, s58, v72
	v_fmac_f32_e32 v11, s58, v73
	v_fmac_f32_e32 v12, s58, v74
	v_fmac_f32_e32 v13, s58, v75
	v_fmac_f32_e32 v20, s62, v72
	v_fmac_f32_e32 v21, s62, v73
	v_fmac_f32_e32 v14, s62, v74
	v_fmac_f32_e32 v15, s62, v75
	v_fmac_f32_e32 v22, s94, v72
	v_fmac_f32_e32 v23, s94, v73
	v_fmac_f32_e32 v16, s94, v74
	v_fmac_f32_e32 v17, s94, v75
	v_fmac_f32_e32 v24, s98, v72
	v_fmac_f32_e32 v25, s98, v73
	v_fmac_f32_e32 v18, s98, v74
	v_fmac_f32_e32 v19, s98, v75
	v_mul_f32_e32 v76, s43, v76
	v_mul_f32_e32 v77, s43, v77
	v_mul_f32_e32 v78, s43, v78
	v_mul_f32_e32 v79, s43, v79
	v_fmac_f32_e32 v10, s59, v76
	v_fmac_f32_e32 v11, s59, v77
	v_fmac_f32_e32 v12, s59, v78
	v_fmac_f32_e32 v13, s59, v79
	v_fmac_f32_e32 v20, s63, v76
	v_fmac_f32_e32 v21, s63, v77
	v_fmac_f32_e32 v14, s63, v78
	v_fmac_f32_e32 v15, s63, v79
	v_fmac_f32_e32 v22, s95, v76
	v_fmac_f32_e32 v23, s95, v77
	v_fmac_f32_e32 v16, s95, v78
	v_fmac_f32_e32 v17, s95, v79
	v_fmac_f32_e32 v24, s99, v76
	v_fmac_f32_e32 v25, s99, v77
	v_fmac_f32_e32 v18, s99, v78
	v_fmac_f32_e32 v19, s99, v79
	s_waitcnt lgkmcnt(0)
	s_load_dwordx4 s[40:43], s[32:33], 0x190
	s_load_dwordx4 s[56:59], s[0:1], 0x190
	s_load_dwordx4 s[60:63], s[0:1], 0x390
	s_load_dwordx4 s[92:95], s[0:1], 0x590
	s_load_dwordx4 s[96:99], s[0:1], 0x790
	global_load_dwordx4 v[64:67], v1, s[50:51] offset:-4096
	global_load_dwordx4 v[68:71], v1, s[50:51]
	s_add_u32 s50, s50, 0x2000
	s_addc_u32 s51, s51, 0
	global_load_dwordx4 v[72:75], v1, s[50:51] offset:-4096
	global_load_dwordx4 v[76:79], v1, s[50:51]
	s_add_u32 s50, s50, 0x2000
	s_addc_u32 s51, s51, 0
	s_waitcnt vmcnt(24)
	v_mul_f32_e32 v80, s4, v80
	v_mul_f32_e32 v81, s4, v81
	v_mul_f32_e32 v82, s4, v82
	v_mul_f32_e32 v83, s4, v83
	v_fmac_f32_e32 v10, s12, v80
	v_fmac_f32_e32 v11, s12, v81
	v_fmac_f32_e32 v12, s12, v82
	v_fmac_f32_e32 v13, s12, v83
	v_fmac_f32_e32 v20, s16, v80
	v_fmac_f32_e32 v21, s16, v81
	v_fmac_f32_e32 v14, s16, v82
	v_fmac_f32_e32 v15, s16, v83
	v_fmac_f32_e32 v22, s36, v80
	v_fmac_f32_e32 v23, s36, v81
	v_fmac_f32_e32 v16, s36, v82
	v_fmac_f32_e32 v17, s36, v83
	v_fmac_f32_e32 v24, s64, v80
	v_fmac_f32_e32 v25, s64, v81
	v_fmac_f32_e32 v18, s64, v82
	v_fmac_f32_e32 v19, s64, v83
	v_mul_f32_e32 v84, s5, v84
	v_mul_f32_e32 v85, s5, v85
	v_mul_f32_e32 v86, s5, v86
	v_mul_f32_e32 v87, s5, v87
	v_fmac_f32_e32 v10, s13, v84
	v_fmac_f32_e32 v11, s13, v85
	v_fmac_f32_e32 v12, s13, v86
	v_fmac_f32_e32 v13, s13, v87
	v_fmac_f32_e32 v20, s17, v84
	v_fmac_f32_e32 v21, s17, v85
	v_fmac_f32_e32 v14, s17, v86
	v_fmac_f32_e32 v15, s17, v87
	v_fmac_f32_e32 v22, s37, v84
	v_fmac_f32_e32 v23, s37, v85
	v_fmac_f32_e32 v16, s37, v86
	v_fmac_f32_e32 v17, s37, v87
	v_fmac_f32_e32 v24, s65, v84
	v_fmac_f32_e32 v25, s65, v85
	v_fmac_f32_e32 v18, s65, v86
	v_fmac_f32_e32 v19, s65, v87
	v_mul_f32_e32 v88, s6, v88
	v_mul_f32_e32 v89, s6, v89
	v_mul_f32_e32 v90, s6, v90
	v_mul_f32_e32 v91, s6, v91
	v_fmac_f32_e32 v10, s14, v88
	v_fmac_f32_e32 v11, s14, v89
	v_fmac_f32_e32 v12, s14, v90
	v_fmac_f32_e32 v13, s14, v91
	v_fmac_f32_e32 v20, s18, v88
	v_fmac_f32_e32 v21, s18, v89
	v_fmac_f32_e32 v14, s18, v90
	v_fmac_f32_e32 v15, s18, v91
	v_fmac_f32_e32 v22, s38, v88
	v_fmac_f32_e32 v23, s38, v89
	v_fmac_f32_e32 v16, s38, v90
	v_fmac_f32_e32 v17, s38, v91
	v_fmac_f32_e32 v24, s66, v88
	v_fmac_f32_e32 v25, s66, v89
	v_fmac_f32_e32 v18, s66, v90
	v_fmac_f32_e32 v19, s66, v91
	v_mul_f32_e32 v92, s7, v92
	v_mul_f32_e32 v93, s7, v93
	v_mul_f32_e32 v94, s7, v94
	v_mul_f32_e32 v95, s7, v95
	v_fmac_f32_e32 v10, s15, v92
	v_fmac_f32_e32 v11, s15, v93
	v_fmac_f32_e32 v12, s15, v94
	v_fmac_f32_e32 v13, s15, v95
	v_fmac_f32_e32 v20, s19, v92
	v_fmac_f32_e32 v21, s19, v93
	v_fmac_f32_e32 v14, s19, v94
	v_fmac_f32_e32 v15, s19, v95
	v_fmac_f32_e32 v22, s39, v92
	v_fmac_f32_e32 v23, s39, v93
	v_fmac_f32_e32 v16, s39, v94
	v_fmac_f32_e32 v17, s39, v95
	v_fmac_f32_e32 v24, s67, v92
	v_fmac_f32_e32 v25, s67, v93
	v_fmac_f32_e32 v18, s67, v94
	v_fmac_f32_e32 v19, s67, v95
	s_waitcnt lgkmcnt(0)
; __global__ void __launch_bounds__(512, 2) fwd_kernel(Args a) {
;     ...
;             for (int d = 0; d < 128; ++d) {
;                 const f32x4 wv = *(const f32x4*)(wo + (size_t)d * D) * sc[d];
;                 s0 += wv * pw[d]; s1 += wv * pw[128 + d]; s2 += wv * pw[256 + d]; s3 += wv * pw[384 + d];
;             }
	s_load_dwordx4 s[4:7], s[32:33], 0x1a0
	s_load_dwordx4 s[12:15], s[0:1], 0x1a0
	s_load_dwordx4 s[16:19], s[0:1], 0x3a0
	s_load_dwordx4 s[36:39], s[0:1], 0x5a0
	s_load_dwordx4 s[64:67], s[0:1], 0x7a0
	global_load_dwordx4 v[80:83], v1, s[50:51] offset:-4096
	global_load_dwordx4 v[84:87], v1, s[50:51]
	s_add_u32 s50, s50, 0x2000
	s_addc_u32 s51, s51, 0
	global_load_dwordx4 v[88:91], v1, s[50:51] offset:-4096
	global_load_dwordx4 v[92:95], v1, s[50:51]
	s_add_u32 s50, s50, 0x2000
	s_addc_u32 s51, s51, 0
	s_waitcnt vmcnt(24)
	v_mul_f32_e32 v96, s40, v96
	v_mul_f32_e32 v97, s40, v97
	v_mul_f32_e32 v98, s40, v98
	v_mul_f32_e32 v99, s40, v99
	v_fmac_f32_e32 v10, s56, v96
	v_fmac_f32_e32 v11, s56, v97
	v_fmac_f32_e32 v12, s56, v98
	v_fmac_f32_e32 v13, s56, v99
	v_fmac_f32_e32 v20, s60, v96
	v_fmac_f32_e32 v21, s60, v97
	v_fmac_f32_e32 v14, s60, v98
	v_fmac_f32_e32 v15, s60, v99
	v_fmac_f32_e32 v22, s92, v96
	v_fmac_f32_e32 v23, s92, v97
	v_fmac_f32_e32 v16, s92, v98
	v_fmac_f32_e32 v17, s92, v99
	v_fmac_f32_e32 v24, s96, v96
	v_fmac_f32_e32 v25, s96, v97
	v_fmac_f32_e32 v18, s96, v98
	v_fmac_f32_e32 v19, s96, v99
	v_mul_f32_e32 v100, s41, v100
	v_mul_f32_e32 v101, s41, v101
	v_mul_f32_e32 v102, s41, v102
	v_mul_f32_e32 v103, s41, v103
	v_fmac_f32_e32 v10, s57, v100
	v_fmac_f32_e32 v11, s57, v101
	v_fmac_f32_e32 v12, s57, v102
	v_fmac_f32_e32 v13, s57, v103
	v_fmac_f32_e32 v20, s61, v100
	v_fmac_f32_e32 v21, s61, v101
	v_fmac_f32_e32 v14, s61, v102
	v_fmac_f32_e32 v15, s61, v103
	v_fmac_f32_e32 v22, s93, v100
	v_fmac_f32_e32 v23, s93, v101
	v_fmac_f32_e32 v16, s93, v102
	v_fmac_f32_e32 v17, s93, v103
	v_fmac_f32_e32 v24, s97, v100
	v_fmac_f32_e32 v25, s97, v101
	v_fmac_f32_e32 v18, s97, v102
	v_fmac_f32_e32 v19, s97, v103
	v_mul_f32_e32 v104, s42, v104
	v_mul_f32_e32 v105, s42, v105
	v_mul_f32_e32 v106, s42, v106
	v_mul_f32_e32 v107, s42, v107
	v_fmac_f32_e32 v10, s58, v104
	v_fmac_f32_e32 v11, s58, v105
	v_fmac_f32_e32 v12, s58, v106
	v_fmac_f32_e32 v13, s58, v107
	v_fmac_f32_e32 v20, s62, v104
	v_fmac_f32_e32 v21, s62, v105
	v_fmac_f32_e32 v14, s62, v106
	v_fmac_f32_e32 v15, s62, v107
	v_fmac_f32_e32 v22, s94, v104
	v_fmac_f32_e32 v23, s94, v105
	v_fmac_f32_e32 v16, s94, v106
	v_fmac_f32_e32 v17, s94, v107
	v_fmac_f32_e32 v24, s98, v104
	v_fmac_f32_e32 v25, s98, v105
	v_fmac_f32_e32 v18, s98, v106
	v_fmac_f32_e32 v19, s98, v107
	v_mul_f32_e32 v108, s43, v108
	v_mul_f32_e32 v109, s43, v109
	v_mul_f32_e32 v110, s43, v110
	v_mul_f32_e32 v111, s43, v111
	v_fmac_f32_e32 v10, s59, v108
	v_fmac_f32_e32 v11, s59, v109
	v_fmac_f32_e32 v12, s59, v110
	v_fmac_f32_e32 v13, s59, v111
	v_fmac_f32_e32 v20, s63, v108
	v_fmac_f32_e32 v21, s63, v109
	v_fmac_f32_e32 v14, s63, v110
	v_fmac_f32_e32 v15, s63, v111
	v_fmac_f32_e32 v22, s95, v108
	v_fmac_f32_e32 v23, s95, v109
	v_fmac_f32_e32 v16, s95, v110
	v_fmac_f32_e32 v17, s95, v111
	v_fmac_f32_e32 v24, s99, v108
	v_fmac_f32_e32 v25, s99, v109
	v_fmac_f32_e32 v18, s99, v110
	v_fmac_f32_e32 v19, s99, v111
	s_waitcnt lgkmcnt(0)
	s_load_dwordx4 s[40:43], s[32:33], 0x1b0
	s_load_dwordx4 s[56:59], s[0:1], 0x1b0
	s_load_dwordx4 s[60:63], s[0:1], 0x3b0
	s_load_dwordx4 s[92:95], s[0:1], 0x5b0
	s_load_dwordx4 s[96:99], s[0:1], 0x7b0
	s_waitcnt vmcnt(20)
	v_mul_f32_e32 v112, s4, v112
	v_mul_f32_e32 v113, s4, v113
	v_mul_f32_e32 v114, s4, v114
	v_mul_f32_e32 v115, s4, v115
	v_fmac_f32_e32 v10, s12, v112
	v_fmac_f32_e32 v11, s12, v113
	v_fmac_f32_e32 v12, s12, v114
	v_fmac_f32_e32 v13, s12, v115
	v_fmac_f32_e32 v20, s16, v112
	v_fmac_f32_e32 v21, s16, v113
	v_fmac_f32_e32 v14, s16, v114
	v_fmac_f32_e32 v15, s16, v115
	v_fmac_f32_e32 v22, s36, v112
	v_fmac_f32_e32 v23, s36, v113
	v_fmac_f32_e32 v16, s36, v114
	v_fmac_f32_e32 v17, s36, v115
	v_fmac_f32_e32 v24, s64, v112
	v_fmac_f32_e32 v25, s64, v113
	v_fmac_f32_e32 v18, s64, v114
	v_fmac_f32_e32 v19, s64, v115
	v_mul_f32_e32 v116, s5, v116
	v_mul_f32_e32 v117, s5, v117
	v_mul_f32_e32 v118, s5, v118
	v_mul_f32_e32 v119, s5, v119
	v_fmac_f32_e32 v10, s13, v116
	v_fmac_f32_e32 v11, s13, v117
	v_fmac_f32_e32 v12, s13, v118
	v_fmac_f32_e32 v13, s13, v119
	v_fmac_f32_e32 v20, s17, v116
	v_fmac_f32_e32 v21, s17, v117
	v_fmac_f32_e32 v14, s17, v118
	v_fmac_f32_e32 v15, s17, v119
	v_fmac_f32_e32 v22, s37, v116
	v_fmac_f32_e32 v23, s37, v117
	v_fmac_f32_e32 v16, s37, v118
	v_fmac_f32_e32 v17, s37, v119
	v_fmac_f32_e32 v24, s65, v116
	v_fmac_f32_e32 v25, s65, v117
	v_fmac_f32_e32 v18, s65, v118
	v_fmac_f32_e32 v19, s65, v119
	v_mul_f32_e32 v120, s6, v120
	v_mul_f32_e32 v121, s6, v121
	v_mul_f32_e32 v122, s6, v122
	v_mul_f32_e32 v123, s6, v123
	v_fmac_f32_e32 v10, s14, v120
	v_fmac_f32_e32 v11, s14, v121
	v_fmac_f32_e32 v12, s14, v122
	v_fmac_f32_e32 v13, s14, v123
	v_fmac_f32_e32 v20, s18, v120
	v_fmac_f32_e32 v21, s18, v121
	v_fmac_f32_e32 v14, s18, v122
	v_fmac_f32_e32 v15, s18, v123
	v_fmac_f32_e32 v22, s38, v120
	v_fmac_f32_e32 v23, s38, v121
	v_fmac_f32_e32 v16, s38, v122
	v_fmac_f32_e32 v17, s38, v123
	v_fmac_f32_e32 v24, s66, v120
	v_fmac_f32_e32 v25, s66, v121
	v_fmac_f32_e32 v18, s66, v122
	v_fmac_f32_e32 v19, s66, v123
	v_mul_f32_e32 v124, s7, v124
	v_mul_f32_e32 v125, s7, v125
	v_mul_f32_e32 v126, s7, v126
	v_mul_f32_e32 v127, s7, v127
	v_fmac_f32_e32 v10, s15, v124
	v_fmac_f32_e32 v11, s15, v125
	v_fmac_f32_e32 v12, s15, v126
	v_fmac_f32_e32 v13, s15, v127
	v_fmac_f32_e32 v20, s19, v124
	v_fmac_f32_e32 v21, s19, v125
	v_fmac_f32_e32 v14, s19, v126
	v_fmac_f32_e32 v15, s19, v127
	v_fmac_f32_e32 v22, s39, v124
	v_fmac_f32_e32 v23, s39, v125
	v_fmac_f32_e32 v16, s39, v126
	v_fmac_f32_e32 v17, s39, v127
	v_fmac_f32_e32 v24, s67, v124
	v_fmac_f32_e32 v25, s67, v125
	v_fmac_f32_e32 v18, s67, v126
	v_fmac_f32_e32 v19, s67, v127
	s_waitcnt lgkmcnt(0)
; __global__ void __launch_bounds__(512, 2) fwd_kernel(Args a) {
;     ...
;             for (int d = 0; d < 128; ++d) {
;                 const f32x4 wv = *(const f32x4*)(wo + (size_t)d * D) * sc[d];
;                 s0 += wv * pw[d]; s1 += wv * pw[128 + d]; s2 += wv * pw[256 + d]; s3 += wv * pw[384 + d];
;             }
	s_load_dwordx4 s[4:7], s[32:33], 0x1c0
	s_load_dwordx4 s[12:15], s[0:1], 0x1c0
	s_load_dwordx4 s[16:19], s[0:1], 0x3c0
	s_load_dwordx4 s[36:39], s[0:1], 0x5c0
	s_load_dwordx4 s[64:67], s[0:1], 0x7c0
	s_waitcnt vmcnt(16)
	v_mul_f32_e32 v128, s40, v128
	v_mul_f32_e32 v129, s40, v129
	v_mul_f32_e32 v130, s40, v130
	v_mul_f32_e32 v131, s40, v131
	v_fmac_f32_e32 v10, s56, v128
	v_fmac_f32_e32 v11, s56, v129
	v_fmac_f32_e32 v12, s56, v130
	v_fmac_f32_e32 v13, s56, v131
	v_fmac_f32_e32 v20, s60, v128
	v_fmac_f32_e32 v21, s60, v129
	v_fmac_f32_e32 v14, s60, v130
	v_fmac_f32_e32 v15, s60, v131
	v_fmac_f32_e32 v22, s92, v128
	v_fmac_f32_e32 v23, s92, v129
	v_fmac_f32_e32 v16, s92, v130
	v_fmac_f32_e32 v17, s92, v131
	v_fmac_f32_e32 v24, s96, v128
	v_fmac_f32_e32 v25, s96, v129
	v_fmac_f32_e32 v18, s96, v130
	v_fmac_f32_e32 v19, s96, v131
	v_mul_f32_e32 v132, s41, v132
	v_mul_f32_e32 v133, s41, v133
	v_mul_f32_e32 v134, s41, v134
	v_mul_f32_e32 v135, s41, v135
	v_fmac_f32_e32 v10, s57, v132
	v_fmac_f32_e32 v11, s57, v133
	v_fmac_f32_e32 v12, s57, v134
	v_fmac_f32_e32 v13, s57, v135
	v_fmac_f32_e32 v20, s61, v132
	v_fmac_f32_e32 v21, s61, v133
	v_fmac_f32_e32 v14, s61, v134
	v_fmac_f32_e32 v15, s61, v135
	v_fmac_f32_e32 v22, s93, v132
	v_fmac_f32_e32 v23, s93, v133
	v_fmac_f32_e32 v16, s93, v134
	v_fmac_f32_e32 v17, s93, v135
	v_fmac_f32_e32 v24, s97, v132
	v_fmac_f32_e32 v25, s97, v133
	v_fmac_f32_e32 v18, s97, v134
	v_fmac_f32_e32 v19, s97, v135
	v_mul_f32_e32 v136, s42, v136
	v_mul_f32_e32 v137, s42, v137
	v_mul_f32_e32 v138, s42, v138
	v_mul_f32_e32 v139, s42, v139
	v_fmac_f32_e32 v10, s58, v136
	v_fmac_f32_e32 v11, s58, v137
	v_fmac_f32_e32 v12, s58, v138
	v_fmac_f32_e32 v13, s58, v139
	v_fmac_f32_e32 v20, s62, v136
	v_fmac_f32_e32 v21, s62, v137
	v_fmac_f32_e32 v14, s62, v138
	v_fmac_f32_e32 v15, s62, v139
	v_fmac_f32_e32 v22, s94, v136
	v_fmac_f32_e32 v23, s94, v137
	v_fmac_f32_e32 v16, s94, v138
	v_fmac_f32_e32 v17, s94, v139
	v_fmac_f32_e32 v24, s98, v136
	v_fmac_f32_e32 v25, s98, v137
	v_fmac_f32_e32 v18, s98, v138
	v_fmac_f32_e32 v19, s98, v139
	v_mul_f32_e32 v140, s43, v140
	v_mul_f32_e32 v141, s43, v141
	v_mul_f32_e32 v142, s43, v142
	v_mul_f32_e32 v143, s43, v143
	v_fmac_f32_e32 v10, s59, v140
	v_fmac_f32_e32 v11, s59, v141
	v_fmac_f32_e32 v12, s59, v142
	v_fmac_f32_e32 v13, s59, v143
	v_fmac_f32_e32 v20, s63, v140
	v_fmac_f32_e32 v21, s63, v141
	v_fmac_f32_e32 v14, s63, v142
	v_fmac_f32_e32 v15, s63, v143
	v_fmac_f32_e32 v22, s95, v140
	v_fmac_f32_e32 v23, s95, v141
	v_fmac_f32_e32 v16, s95, v142
	v_fmac_f32_e32 v17, s95, v143
	v_fmac_f32_e32 v24, s99, v140
	v_fmac_f32_e32 v25, s99, v141
	v_fmac_f32_e32 v18, s99, v142
	v_fmac_f32_e32 v19, s99, v143
	s_waitcnt lgkmcnt(0)
	s_load_dwordx4 s[40:43], s[32:33], 0x1d0
	s_load_dwordx4 s[56:59], s[0:1], 0x1d0
	s_load_dwordx4 s[60:63], s[0:1], 0x3d0
	s_load_dwordx4 s[92:95], s[0:1], 0x5d0
	s_load_dwordx4 s[96:99], s[0:1], 0x7d0
	s_waitcnt vmcnt(12)
	v_mul_f32_e32 v32, s4, v32
	v_mul_f32_e32 v33, s4, v33
	v_mul_f32_e32 v34, s4, v34
	v_mul_f32_e32 v35, s4, v35
	v_fmac_f32_e32 v10, s12, v32
	v_fmac_f32_e32 v11, s12, v33
	v_fmac_f32_e32 v12, s12, v34
	v_fmac_f32_e32 v13, s12, v35
	v_fmac_f32_e32 v20, s16, v32
	v_fmac_f32_e32 v21, s16, v33
	v_fmac_f32_e32 v14, s16, v34
	v_fmac_f32_e32 v15, s16, v35
	v_fmac_f32_e32 v22, s36, v32
	v_fmac_f32_e32 v23, s36, v33
	v_fmac_f32_e32 v16, s36, v34
	v_fmac_f32_e32 v17, s36, v35
	v_fmac_f32_e32 v24, s64, v32
	v_fmac_f32_e32 v25, s64, v33
	v_fmac_f32_e32 v18, s64, v34
	v_fmac_f32_e32 v19, s64, v35
	v_mul_f32_e32 v36, s5, v36
	v_mul_f32_e32 v37, s5, v37
	v_mul_f32_e32 v38, s5, v38
	v_mul_f32_e32 v39, s5, v39
	v_fmac_f32_e32 v10, s13, v36
	v_fmac_f32_e32 v11, s13, v37
	v_fmac_f32_e32 v12, s13, v38
	v_fmac_f32_e32 v13, s13, v39
	v_fmac_f32_e32 v20, s17, v36
	v_fmac_f32_e32 v21, s17, v37
	v_fmac_f32_e32 v14, s17, v38
	v_fmac_f32_e32 v15, s17, v39
	v_fmac_f32_e32 v22, s37, v36
	v_fmac_f32_e32 v23, s37, v37
	v_fmac_f32_e32 v16, s37, v38
	v_fmac_f32_e32 v17, s37, v39
	v_fmac_f32_e32 v24, s65, v36
	v_fmac_f32_e32 v25, s65, v37
	v_fmac_f32_e32 v18, s65, v38
	v_fmac_f32_e32 v19, s65, v39
	v_mul_f32_e32 v40, s6, v40
	v_mul_f32_e32 v41, s6, v41
	v_mul_f32_e32 v42, s6, v42
	v_mul_f32_e32 v43, s6, v43
	v_fmac_f32_e32 v10, s14, v40
	v_fmac_f32_e32 v11, s14, v41
	v_fmac_f32_e32 v12, s14, v42
	v_fmac_f32_e32 v13, s14, v43
	v_fmac_f32_e32 v20, s18, v40
	v_fmac_f32_e32 v21, s18, v41
	v_fmac_f32_e32 v14, s18, v42
	v_fmac_f32_e32 v15, s18, v43
	v_fmac_f32_e32 v22, s38, v40
	v_fmac_f32_e32 v23, s38, v41
	v_fmac_f32_e32 v16, s38, v42
	v_fmac_f32_e32 v17, s38, v43
	v_fmac_f32_e32 v24, s66, v40
	v_fmac_f32_e32 v25, s66, v41
	v_fmac_f32_e32 v18, s66, v42
	v_fmac_f32_e32 v19, s66, v43
	v_mul_f32_e32 v44, s7, v44
	v_mul_f32_e32 v45, s7, v45
	v_mul_f32_e32 v46, s7, v46
	v_mul_f32_e32 v47, s7, v47
	v_fmac_f32_e32 v10, s15, v44
	v_fmac_f32_e32 v11, s15, v45
	v_fmac_f32_e32 v12, s15, v46
	v_fmac_f32_e32 v13, s15, v47
	v_fmac_f32_e32 v20, s19, v44
	v_fmac_f32_e32 v21, s19, v45
	v_fmac_f32_e32 v14, s19, v46
	v_fmac_f32_e32 v15, s19, v47
	v_fmac_f32_e32 v22, s39, v44
	v_fmac_f32_e32 v23, s39, v45
	v_fmac_f32_e32 v16, s39, v46
	v_fmac_f32_e32 v17, s39, v47
	v_fmac_f32_e32 v24, s67, v44
	v_fmac_f32_e32 v25, s67, v45
	v_fmac_f32_e32 v18, s67, v46
	v_fmac_f32_e32 v19, s67, v47
	s_waitcnt lgkmcnt(0)
	s_load_dwordx4 s[4:7], s[32:33], 0x1e0
	s_load_dwordx4 s[12:15], s[0:1], 0x1e0
	s_load_dwordx4 s[16:19], s[0:1], 0x3e0
	s_load_dwordx4 s[36:39], s[0:1], 0x5e0
	s_load_dwordx4 s[64:67], s[0:1], 0x7e0
	s_waitcnt vmcnt(8)
; __global__ void __launch_bounds__(512, 2) fwd_kernel(Args a) {
;     ...
;             for (int d = 0; d < 128; ++d) {
;                 const f32x4 wv = *(const f32x4*)(wo + (size_t)d * D) * sc[d];
;                 s0 += wv * pw[d]; s1 += wv * pw[128 + d]; s2 += wv * pw[256 + d]; s3 += wv * pw[384 + d];
	v_mul_f32_e32 v48, s40, v48
	v_mul_f32_e32 v49, s40, v49
	v_mul_f32_e32 v50, s40, v50
	v_mul_f32_e32 v51, s40, v51
	v_fmac_f32_e32 v10, s56, v48
	v_fmac_f32_e32 v11, s56, v49
	v_fmac_f32_e32 v12, s56, v50
	v_fmac_f32_e32 v13, s56, v51
	v_fmac_f32_e32 v20, s60, v48
	v_fmac_f32_e32 v21, s60, v49
	v_fmac_f32_e32 v14, s60, v50
	v_fmac_f32_e32 v15, s60, v51
	v_fmac_f32_e32 v22, s92, v48
	v_fmac_f32_e32 v23, s92, v49
	v_fmac_f32_e32 v16, s92, v50
	v_fmac_f32_e32 v17, s92, v51
	v_fmac_f32_e32 v24, s96, v48
	v_fmac_f32_e32 v25, s96, v49
	v_fmac_f32_e32 v18, s96, v50
	v_fmac_f32_e32 v19, s96, v51
	v_mul_f32_e32 v52, s41, v52
	v_mul_f32_e32 v53, s41, v53
	v_mul_f32_e32 v54, s41, v54
	v_mul_f32_e32 v55, s41, v55
	v_fmac_f32_e32 v10, s57, v52
	v_fmac_f32_e32 v11, s57, v53
	v_fmac_f32_e32 v12, s57, v54
	v_fmac_f32_e32 v13, s57, v55
	v_fmac_f32_e32 v20, s61, v52
	v_fmac_f32_e32 v21, s61, v53
	v_fmac_f32_e32 v14, s61, v54
	v_fmac_f32_e32 v15, s61, v55
	v_fmac_f32_e32 v22, s93, v52
	v_fmac_f32_e32 v23, s93, v53
	v_fmac_f32_e32 v16, s93, v54
	v_fmac_f32_e32 v17, s93, v55
	v_fmac_f32_e32 v24, s97, v52
	v_fmac_f32_e32 v25, s97, v53
	v_fmac_f32_e32 v18, s97, v54
	v_fmac_f32_e32 v19, s97, v55
	v_mul_f32_e32 v56, s42, v56
	v_mul_f32_e32 v57, s42, v57
	v_mul_f32_e32 v58, s42, v58
	v_mul_f32_e32 v59, s42, v59
	v_fmac_f32_e32 v10, s58, v56
	v_fmac_f32_e32 v11, s58, v57
	v_fmac_f32_e32 v12, s58, v58
	v_fmac_f32_e32 v13, s58, v59
	v_fmac_f32_e32 v20, s62, v56
	v_fmac_f32_e32 v21, s62, v57
	v_fmac_f32_e32 v14, s62, v58
	v_fmac_f32_e32 v15, s62, v59
	v_fmac_f32_e32 v22, s94, v56
	v_fmac_f32_e32 v23, s94, v57
	v_fmac_f32_e32 v16, s94, v58
	v_fmac_f32_e32 v17, s94, v59
	v_fmac_f32_e32 v24, s98, v56
	v_fmac_f32_e32 v25, s98, v57
	v_fmac_f32_e32 v18, s98, v58
	v_fmac_f32_e32 v19, s98, v59
	v_mul_f32_e32 v60, s43, v60
	v_mul_f32_e32 v61, s43, v61
	v_mul_f32_e32 v62, s43, v62
	v_mul_f32_e32 v63, s43, v63
	v_fmac_f32_e32 v10, s59, v60
	v_fmac_f32_e32 v11, s59, v61
	v_fmac_f32_e32 v12, s59, v62
	v_fmac_f32_e32 v13, s59, v63
	v_fmac_f32_e32 v20, s63, v60
	v_fmac_f32_e32 v21, s63, v61
	v_fmac_f32_e32 v14, s63, v62
	v_fmac_f32_e32 v15, s63, v63
	v_fmac_f32_e32 v22, s95, v60
	v_fmac_f32_e32 v23, s95, v61
	v_fmac_f32_e32 v16, s95, v62
	v_fmac_f32_e32 v17, s95, v63
	v_fmac_f32_e32 v24, s99, v60
	v_fmac_f32_e32 v25, s99, v61
	v_fmac_f32_e32 v18, s99, v62
	v_fmac_f32_e32 v19, s99, v63
	s_waitcnt lgkmcnt(0)
	s_load_dwordx4 s[40:43], s[32:33], 0x1f0
	s_load_dwordx4 s[56:59], s[0:1], 0x1f0
	s_load_dwordx4 s[60:63], s[0:1], 0x3f0
	s_load_dwordx4 s[92:95], s[0:1], 0x5f0
	s_load_dwordx4 s[96:99], s[0:1], 0x7f0
	s_waitcnt vmcnt(4)
	v_mul_f32_e32 v64, s4, v64
	v_mul_f32_e32 v65, s4, v65
	v_mul_f32_e32 v66, s4, v66
	v_mul_f32_e32 v67, s4, v67
	v_fmac_f32_e32 v10, s12, v64
	v_fmac_f32_e32 v11, s12, v65
	v_fmac_f32_e32 v12, s12, v66
	v_fmac_f32_e32 v13, s12, v67
	v_fmac_f32_e32 v20, s16, v64
	v_fmac_f32_e32 v21, s16, v65
	v_fmac_f32_e32 v14, s16, v66
	v_fmac_f32_e32 v15, s16, v67
	v_fmac_f32_e32 v22, s36, v64
	v_fmac_f32_e32 v23, s36, v65
	v_fmac_f32_e32 v16, s36, v66
	v_fmac_f32_e32 v17, s36, v67
	v_fmac_f32_e32 v24, s64, v64
	v_fmac_f32_e32 v25, s64, v65
	v_fmac_f32_e32 v18, s64, v66
	v_fmac_f32_e32 v19, s64, v67
	v_mul_f32_e32 v68, s5, v68
	v_mul_f32_e32 v69, s5, v69
	v_mul_f32_e32 v70, s5, v70
	v_mul_f32_e32 v71, s5, v71
	v_fmac_f32_e32 v10, s13, v68
	v_fmac_f32_e32 v11, s13, v69
	v_fmac_f32_e32 v12, s13, v70
	v_fmac_f32_e32 v13, s13, v71
	v_fmac_f32_e32 v20, s17, v68
	v_fmac_f32_e32 v21, s17, v69
	v_fmac_f32_e32 v14, s17, v70
	v_fmac_f32_e32 v15, s17, v71
	v_fmac_f32_e32 v22, s37, v68
	v_fmac_f32_e32 v23, s37, v69
	v_fmac_f32_e32 v16, s37, v70
	v_fmac_f32_e32 v17, s37, v71
	v_fmac_f32_e32 v24, s65, v68
	v_fmac_f32_e32 v25, s65, v69
	v_fmac_f32_e32 v18, s65, v70
	v_fmac_f32_e32 v19, s65, v71
	v_mul_f32_e32 v72, s6, v72
	v_mul_f32_e32 v73, s6, v73
	v_mul_f32_e32 v74, s6, v74
	v_mul_f32_e32 v75, s6, v75
	v_fmac_f32_e32 v10, s14, v72
	v_fmac_f32_e32 v11, s14, v73
	v_fmac_f32_e32 v12, s14, v74
	v_fmac_f32_e32 v13, s14, v75
	v_fmac_f32_e32 v20, s18, v72
	v_fmac_f32_e32 v21, s18, v73
	v_fmac_f32_e32 v14, s18, v74
	v_fmac_f32_e32 v15, s18, v75
	v_fmac_f32_e32 v22, s38, v72
	v_fmac_f32_e32 v23, s38, v73
	v_fmac_f32_e32 v16, s38, v74
	v_fmac_f32_e32 v17, s38, v75
	v_fmac_f32_e32 v24, s66, v72
	v_fmac_f32_e32 v25, s66, v73
	v_fmac_f32_e32 v18, s66, v74
	v_fmac_f32_e32 v19, s66, v75
	v_mul_f32_e32 v76, s7, v76
	v_mul_f32_e32 v77, s7, v77
	v_mul_f32_e32 v78, s7, v78
	v_mul_f32_e32 v79, s7, v79
	v_fmac_f32_e32 v10, s15, v76
	v_fmac_f32_e32 v11, s15, v77
	v_fmac_f32_e32 v12, s15, v78
	v_fmac_f32_e32 v13, s15, v79
	v_fmac_f32_e32 v20, s19, v76
	v_fmac_f32_e32 v21, s19, v77
	v_fmac_f32_e32 v14, s19, v78
	v_fmac_f32_e32 v15, s19, v79
	v_fmac_f32_e32 v22, s39, v76
	v_fmac_f32_e32 v23, s39, v77
	v_fmac_f32_e32 v16, s39, v78
	v_fmac_f32_e32 v17, s39, v79
	v_fmac_f32_e32 v24, s67, v76
	v_fmac_f32_e32 v25, s67, v77
	v_fmac_f32_e32 v18, s67, v78
	v_fmac_f32_e32 v19, s67, v79
	s_waitcnt lgkmcnt(0)
; __device__ __forceinline__ unsigned cvt_pk_bf16(float lo, float hi) { unsigned r; asm volatile("v_cvt_pk_bf16_f32 %0, %1, %2" : "=v"(r) : "v"(lo), "v"(hi)); return r; }
; __global__ void __launch_bounds__(512, 2) fwd_kernel(Args a) {
;     ...
;             for (int d = 0; d < 128; ++d) {
;                 const f32x4 wv = *(const f32x4*)(wo + (size_t)d * D) * sc[d];
;                 s0 += wv * pw[d]; s1 += wv * pw[128 + d]; s2 += wv * pw[256 + d]; s3 += wv * pw[384 + d];
;             }
; #pragma unroll
;             for (int e = 0; e < 4; ++e) {
;                 v2u w; w.x = cvt_pk_bf16(s0[e], s1[e]); w.y = cvt_pk_bf16(s2[e], s3[e]);
;                 *(v2u*)(WMIX + (size_t)(n4 + e) * D + 512 + gc0) = w;
;             }
	s_waitcnt vmcnt(0)
	v_mul_f32_e32 v80, s40, v80
	v_mul_f32_e32 v81, s40, v81
	v_mul_f32_e32 v82, s40, v82
	v_mul_f32_e32 v83, s40, v83
	v_fmac_f32_e32 v10, s56, v80
	v_fmac_f32_e32 v11, s56, v81
	v_fmac_f32_e32 v12, s56, v82
	v_fmac_f32_e32 v13, s56, v83
	v_fmac_f32_e32 v20, s60, v80
	v_fmac_f32_e32 v21, s60, v81
	v_fmac_f32_e32 v14, s60, v82
	v_fmac_f32_e32 v15, s60, v83
	v_fmac_f32_e32 v22, s92, v80
	v_fmac_f32_e32 v23, s92, v81
	v_fmac_f32_e32 v16, s92, v82
	v_fmac_f32_e32 v17, s92, v83
	v_fmac_f32_e32 v24, s96, v80
	v_fmac_f32_e32 v25, s96, v81
	v_fmac_f32_e32 v18, s96, v82
	v_fmac_f32_e32 v19, s96, v83
	v_mul_f32_e32 v84, s41, v84
	v_mul_f32_e32 v85, s41, v85
	v_mul_f32_e32 v86, s41, v86
	v_mul_f32_e32 v87, s41, v87
	v_fmac_f32_e32 v10, s57, v84
	v_fmac_f32_e32 v11, s57, v85
	v_fmac_f32_e32 v12, s57, v86
	v_fmac_f32_e32 v13, s57, v87
	v_fmac_f32_e32 v20, s61, v84
	v_fmac_f32_e32 v21, s61, v85
	v_fmac_f32_e32 v14, s61, v86
	v_fmac_f32_e32 v15, s61, v87
	v_fmac_f32_e32 v22, s93, v84
	v_fmac_f32_e32 v23, s93, v85
	v_fmac_f32_e32 v16, s93, v86
	v_fmac_f32_e32 v17, s93, v87
	v_fmac_f32_e32 v24, s97, v84
	v_fmac_f32_e32 v25, s97, v85
	v_fmac_f32_e32 v18, s97, v86
	v_fmac_f32_e32 v19, s97, v87
	v_mul_f32_e32 v88, s42, v88
	v_mul_f32_e32 v89, s42, v89
	v_mul_f32_e32 v90, s42, v90
	v_mul_f32_e32 v91, s42, v91
	v_fmac_f32_e32 v10, s58, v88
	v_fmac_f32_e32 v11, s58, v89
	v_fmac_f32_e32 v12, s58, v90
	v_fmac_f32_e32 v13, s58, v91
	v_fmac_f32_e32 v20, s62, v88
	v_fmac_f32_e32 v21, s62, v89
	v_fmac_f32_e32 v14, s62, v90
	v_fmac_f32_e32 v15, s62, v91
	v_fmac_f32_e32 v22, s94, v88
	v_fmac_f32_e32 v23, s94, v89
	v_fmac_f32_e32 v16, s94, v90
	v_fmac_f32_e32 v17, s94, v91
	v_fmac_f32_e32 v24, s98, v88
	v_fmac_f32_e32 v25, s98, v89
	v_fmac_f32_e32 v18, s98, v90
	v_fmac_f32_e32 v19, s98, v91
	v_mul_f32_e32 v92, s43, v92
	v_mul_f32_e32 v93, s43, v93
	v_mul_f32_e32 v94, s43, v94
	v_mul_f32_e32 v95, s43, v95
	v_fmac_f32_e32 v10, s59, v92
	v_fmac_f32_e32 v11, s59, v93
	v_fmac_f32_e32 v12, s59, v94
	v_fmac_f32_e32 v13, s59, v95
	v_fmac_f32_e32 v20, s63, v92
	v_fmac_f32_e32 v21, s63, v93
	v_fmac_f32_e32 v14, s63, v94
	v_fmac_f32_e32 v15, s63, v95
	v_fmac_f32_e32 v22, s95, v92
	v_fmac_f32_e32 v23, s95, v93
	v_fmac_f32_e32 v16, s95, v94
	v_fmac_f32_e32 v17, s95, v95
	v_fmac_f32_e32 v24, s99, v92
	v_fmac_f32_e32 v25, s99, v93
	v_fmac_f32_e32 v18, s99, v94
	v_fmac_f32_e32 v19, s99, v95
	v_lshlrev_b32_e32 v0, 13, v0
	v_and_b32_e32 v0, 0x1fe000, v0
	v_mov_b32_e32 v1, 0
	v_lshl_add_u64 v[6:7], s[10:11], 0, v[0:1]
	v_lshlrev_b32_e32 v0, 1, v2
	v_lshl_add_u64 v[0:1], v[6:7], 0, v[0:1]
	s_mov_b32 s0, 0x280000
	v_add_co_u32_e32 v2, vcc, s0, v0
	v_cvt_pk_bf16_f32 v4, v10, v20
	v_cvt_pk_bf16_f32 v5, v22, v24
	s_nop 1
	v_addc_co_u32_e32 v3, vcc, 0, v1, vcc
	v_add_co_u32_e32 v0, vcc, 0x281000, v0
	global_store_dwordx2 v[2:3], v[4:5], off offset:1024
	v_cvt_pk_bf16_f32 v4, v11, v21
	v_cvt_pk_bf16_f32 v5, v23, v25
	global_store_dwordx2 v[2:3], v[4:5], off offset:3072
	v_cvt_pk_bf16_f32 v2, v12, v14
	v_cvt_pk_bf16_f32 v3, v16, v18
	v_addc_co_u32_e32 v1, vcc, 0, v1, vcc
	global_store_dwordx2 v[0:1], v[2:3], off offset:1024
	v_cvt_pk_bf16_f32 v2, v13, v15
	v_cvt_pk_bf16_f32 v3, v17, v19
	global_store_dwordx2 v[0:1], v[2:3], off offset:3072

; __global__ void __launch_bounds__(512, 2) fwd_kernel(Args a) {
	.amdhsa_kernel _Z10fwd_kernel4Args
		.amdhsa_group_segment_fixed_size 0
		.amdhsa_private_segment_fixed_size 0
		.amdhsa_kernarg_size 480
		.amdhsa_user_sgpr_count 2
		.amdhsa_user_sgpr_dispatch_ptr 0
		.amdhsa_user_sgpr_queue_ptr 0
		.amdhsa_user_sgpr_kernarg_segment_ptr 1
		.amdhsa_user_sgpr_dispatch_id 0
		.amdhsa_user_sgpr_kernarg_preload_length 0
		.amdhsa_user_sgpr_kernarg_preload_offset 0
		.amdhsa_user_sgpr_private_segment_size 0
		.amdhsa_uses_dynamic_stack 0
		.amdhsa_enable_private_segment 0
		.amdhsa_system_sgpr_workgroup_id_x 1
		.amdhsa_system_sgpr_workgroup_id_y 0
		.amdhsa_system_sgpr_workgroup_id_z 0
		.amdhsa_system_sgpr_workgroup_info 0
		.amdhsa_system_vgpr_workitem_id 2
		.amdhsa_next_free_vgpr 256
		.amdhsa_next_free_sgpr 102
		.amdhsa_accum_offset 256
		.amdhsa_reserve_vcc 1
		.amdhsa_float_round_mode_32 0
		.amdhsa_float_round_mode_16_64 0
		.amdhsa_float_denorm_mode_32 3
		.amdhsa_float_denorm_mode_16_64 3
		.amdhsa_dx10_clamp 1
		.amdhsa_ieee_mode 1
		.amdhsa_fp16_overflow 0
		.amdhsa_tg_split 0
		.amdhsa_exception_fp_ieee_invalid_op 0
		.amdhsa_exception_fp_denorm_src 0
		.amdhsa_exception_fp_ieee_div_zero 0
		.amdhsa_exception_fp_ieee_overflow 0
		.amdhsa_exception_fp_ieee_underflow 0
		.amdhsa_exception_fp_ieee_inexact 0
		.amdhsa_exception_int_div_zero 0
	.end_amdhsa_kernel

; __global__ void __launch_bounds__(512, 2) fwd_kernel(Args a) {
amdhsa.kernels:
  - .agpr_count:     0
    .args:
      - .offset:         0
        .size:           224
        .value_kind:     by_value
      - .offset:         224
        .size:           4
        .value_kind:     hidden_block_count_x
      - .offset:         228
        .size:           4
        .value_kind:     hidden_block_count_y
      - .offset:         232
        .size:           4
        .value_kind:     hidden_block_count_z
      - .offset:         236
        .size:           2
        .value_kind:     hidden_group_size_x
      - .offset:         238
        .size:           2
        .value_kind:     hidden_group_size_y
      - .offset:         240
        .size:           2
        .value_kind:     hidden_group_size_z
      - .offset:         242
        .size:           2
        .value_kind:     hidden_remainder_x
      - .offset:         244
        .size:           2
        .value_kind:     hidden_remainder_y
      - .offset:         246
        .size:           2
        .value_kind:     hidden_remainder_z
      - .offset:         264
        .size:           8
        .value_kind:     hidden_global_offset_x
      - .offset:         272
        .size:           8
        .value_kind:     hidden_global_offset_y
      - .offset:         280
        .size:           8
        .value_kind:     hidden_global_offset_z
      - .offset:         288
        .size:           2
        .value_kind:     hidden_grid_dims
      - .offset:         312
        .size:           8
        .value_kind:     hidden_multigrid_sync_arg
      - .offset:         344
        .size:           4
        .value_kind:     hidden_dynamic_lds_size
    .group_segment_fixed_size: 0
    .kernarg_segment_align: 8
    .kernarg_segment_size: 480
    .language:       OpenCL C
    .language_version:
      - 2
      - 0
    .max_flat_workgroup_size: 512
    .name:           _Z10fwd_kernel4Args
    .private_segment_fixed_size: 0
    .sgpr_count:     108
    .sgpr_spill_count: 25
    .symbol:         _Z10fwd_kernel4Args.kd
    .uniform_work_group_size: 1
    .uses_dynamic_stack: false
    .vgpr_count:     256
    .vgpr_spill_count: 0
    .wavefront_size: 64
